# K loops: pads between consecutive LDS-DMA issue blocks removed (90 slots), on top of boundary + scheduler + barrier changes
# baseline (speedup 1.0000x reference)
.Lnb_p1:
	s_add_i32 s7, s4, 0xfff84000
	s_cmp_eq_u32 s6, 28
	s_cselect_b32 s17, s0, s7
	s_cselect_b32 s16, s1, s5
	s_or_b32 s7, s17, 0x4000
	s_mov_b32 m0, s79
	s_nop 0
	buffer_load_dwordx4 v242, s[24:27], s4 offen lds
	s_mov_b32 m0, s83
	s_nop 0
	buffer_load_dwordx4 v243, s[24:27], s4 offen lds
	s_waitcnt vmcnt(24)
	s_waitcnt lgkmcnt(0)
	s_barrier
	s_setprio 1
	s_waitcnt lgkmcnt(7)
	v_mfma_f32_16x16x32_bf16 v[180:183], v[16:19], v[192:195], 0
	v_mfma_f32_16x16x32_bf16 v[164:167], v[24:27], v[192:195], 0
	s_waitcnt lgkmcnt(5)
	v_mfma_f32_16x16x32_bf16 v[148:151], v[16:19], v[200:203], 0
	v_mfma_f32_16x16x32_bf16 v[140:143], v[24:27], v[200:203], 0
	s_waitcnt lgkmcnt(3)
	v_mfma_f32_16x16x32_bf16 v[132:135], v[16:19], v[220:223], 0
	v_mfma_f32_16x16x32_bf16 v[124:127], v[24:27], v[220:223], 0
	s_waitcnt lgkmcnt(1)
	v_mfma_f32_16x16x32_bf16 v[116:119], v[16:19], v[228:231], 0
	v_mfma_f32_16x16x32_bf16 v[108:111], v[24:27], v[228:231], 0
	v_mfma_f32_16x16x32_bf16 v[180:183], v[20:23], v[196:199], v[180:183]
	v_mfma_f32_16x16x32_bf16 v[164:167], v[28:31], v[196:199], v[164:167]
	v_mfma_f32_16x16x32_bf16 v[148:151], v[20:23], v[204:207], v[148:151]
	v_mfma_f32_16x16x32_bf16 v[140:143], v[28:31], v[204:207], v[140:143]
	v_mfma_f32_16x16x32_bf16 v[132:135], v[20:23], v[224:227], v[132:135]
	v_mfma_f32_16x16x32_bf16 v[124:127], v[28:31], v[224:227], v[124:127]
	s_waitcnt lgkmcnt(0)
	v_mfma_f32_16x16x32_bf16 v[116:119], v[20:23], v[246:249], v[116:119]
	v_mfma_f32_16x16x32_bf16 v[108:111], v[28:31], v[246:249], v[108:111]
	s_setprio 0
	s_setprio 1
	v_mfma_f32_16x16x32_bf16 v[172:175], v[152:155], v[192:195], 0
	v_mfma_f32_16x16x32_bf16 v[156:159], v[168:171], v[192:195], 0
	v_mfma_f32_16x16x32_bf16 v[144:147], v[152:155], v[200:203], 0
	v_mfma_f32_16x16x32_bf16 v[136:139], v[168:171], v[200:203], 0
	v_mfma_f32_16x16x32_bf16 v[128:131], v[152:155], v[220:223], 0
	v_mfma_f32_16x16x32_bf16 v[120:123], v[168:171], v[220:223], 0
	v_mfma_f32_16x16x32_bf16 v[112:115], v[152:155], v[228:231], 0
	v_mfma_f32_16x16x32_bf16 v[104:107], v[168:171], v[228:231], 0
	v_mfma_f32_16x16x32_bf16 v[172:175], v[160:163], v[196:199], v[172:175]
	v_mfma_f32_16x16x32_bf16 v[156:159], v[176:179], v[196:199], v[156:159]
	v_mfma_f32_16x16x32_bf16 v[144:147], v[160:163], v[204:207], v[144:147]
	v_mfma_f32_16x16x32_bf16 v[136:139], v[176:179], v[204:207], v[136:139]
	v_mfma_f32_16x16x32_bf16 v[128:131], v[160:163], v[224:227], v[128:131]
	v_mfma_f32_16x16x32_bf16 v[120:123], v[176:179], v[224:227], v[120:123]
	v_mfma_f32_16x16x32_bf16 v[112:115], v[160:163], v[246:249], v[112:115]
	v_mfma_f32_16x16x32_bf16 v[104:107], v[176:179], v[246:249], v[104:107]
	s_setprio 0
	s_barrier
	ds_read_b128 v[192:195], v245 offset:16384
	ds_read_b128 v[196:199], v245 offset:17408
	ds_read_b128 v[200:203], v245 offset:18432
	ds_read_b128 v[204:207], v245 offset:19456
	ds_read_b128 v[220:223], v245 offset:20480
	ds_read_b128 v[224:227], v245 offset:21504
	ds_read_b128 v[228:231], v245 offset:22528
	ds_read_b128 v[246:249], v245 offset:23552
	s_mov_b32 m0, s51
	s_nop 0
	buffer_load_dwordx4 v242, s[56:59], s16 offen lds
	s_add_i32 s18, s16, 0x80000
	s_mov_b32 m0, s52
	s_nop 0
	buffer_load_dwordx4 v243, s[56:59], s16 offen lds
	s_mov_b32 m0, s53
	s_nop 0
	buffer_load_dwordx4 v242, s[56:59], s18 offen lds
	s_mov_b32 m0, s55
	s_nop 0
	buffer_load_dwordx4 v243, s[56:59], s18 offen lds
	s_mov_b32 m0, s31
	s_nop 0
	buffer_load_dwordx4 v242, s[24:27], s17 offen lds
	s_mov_b32 m0, s68
	s_nop 0
	buffer_load_dwordx4 v243, s[24:27], s17 offen lds
	s_waitcnt vmcnt(24)
	s_waitcnt lgkmcnt(0)
	s_barrier
	s_setprio 1
	s_waitcnt lgkmcnt(7)
	v_mfma_f32_16x16x32_bf16 v[76:79], v[16:19], v[192:195], 0
	v_mfma_f32_16x16x32_bf16 v[68:71], v[24:27], v[192:195], 0
	s_waitcnt lgkmcnt(5)
	v_mfma_f32_16x16x32_bf16 v[60:63], v[16:19], v[200:203], 0
	v_mfma_f32_16x16x32_bf16 v[52:55], v[24:27], v[200:203], 0
	s_waitcnt lgkmcnt(3)
	v_mfma_f32_16x16x32_bf16 v[44:47], v[16:19], v[220:223], 0
	v_mfma_f32_16x16x32_bf16 v[36:39], v[24:27], v[220:223], 0
	s_waitcnt lgkmcnt(1)
	v_mfma_f32_16x16x32_bf16 v[12:15], v[16:19], v[228:231], 0
	v_mfma_f32_16x16x32_bf16 v[4:7], v[24:27], v[228:231], 0
	v_mfma_f32_16x16x32_bf16 v[76:79], v[20:23], v[196:199], v[76:79]
	v_mfma_f32_16x16x32_bf16 v[68:71], v[28:31], v[196:199], v[68:71]
	v_mfma_f32_16x16x32_bf16 v[60:63], v[20:23], v[204:207], v[60:63]
	v_mfma_f32_16x16x32_bf16 v[52:55], v[28:31], v[204:207], v[52:55]
	v_mfma_f32_16x16x32_bf16 v[44:47], v[20:23], v[224:227], v[44:47]
	v_mfma_f32_16x16x32_bf16 v[36:39], v[28:31], v[224:227], v[36:39]
	s_waitcnt lgkmcnt(0)
	v_mfma_f32_16x16x32_bf16 v[12:15], v[20:23], v[246:249], v[12:15]
	v_mfma_f32_16x16x32_bf16 v[4:7], v[28:31], v[246:249], v[4:7]
	s_setprio 0
	s_setprio 1
	v_mfma_f32_16x16x32_bf16 v[40:43], v[152:155], v[220:223], 0
	v_mfma_f32_16x16x32_bf16 v[32:35], v[168:171], v[220:223], 0
	v_mfma_f32_16x16x32_bf16 v[8:11], v[152:155], v[228:231], 0
	v_mfma_f32_16x16x32_bf16 v[0:3], v[168:171], v[228:231], 0
	v_mfma_f32_16x16x32_bf16 v[16:19], v[152:155], v[192:195], 0
	v_mfma_f32_16x16x32_bf16 v[20:23], v[168:171], v[192:195], 0
	v_mfma_f32_16x16x32_bf16 v[24:27], v[152:155], v[200:203], 0
	v_mfma_f32_16x16x32_bf16 v[28:31], v[168:171], v[200:203], 0
	v_mfma_f32_16x16x32_bf16 v[40:43], v[160:163], v[224:227], v[40:43]
	v_mfma_f32_16x16x32_bf16 v[32:35], v[176:179], v[224:227], v[32:35]
	v_mfma_f32_16x16x32_bf16 v[8:11], v[160:163], v[246:249], v[8:11]
	v_mfma_f32_16x16x32_bf16 v[0:3], v[176:179], v[246:249], v[0:3]
	v_mfma_f32_16x16x32_bf16 v[16:19], v[160:163], v[196:199], v[16:19]
	v_mfma_f32_16x16x32_bf16 v[20:23], v[176:179], v[196:199], v[20:23]
	v_mfma_f32_16x16x32_bf16 v[24:27], v[160:163], v[204:207], v[24:27]
	v_mfma_f32_16x16x32_bf16 v[28:31], v[176:179], v[204:207], v[28:31]
	s_setprio 0
	s_barrier
	v_add_u32_e32 v72, 0x18000, v83
	v_add_u32_e32 v80, 0x1c000, v83
	ds_read_b128 v[48:51], v72
	ds_read_b128 v[56:59], v72 offset:1024
	ds_read_b128 v[64:67], v72 offset:2048
	ds_read_b128 v[72:75], v72 offset:3072
	ds_read_b128 v[152:155], v80
	ds_read_b128 v[160:163], v80 offset:1024
	ds_read_b128 v[168:171], v80 offset:2048
	ds_read_b128 v[176:179], v80 offset:3072
	ds_read_b128 v[192:195], v245 offset:32768
	ds_read_b128 v[196:199], v245 offset:33792
	ds_read_b128 v[200:203], v245 offset:34816
	ds_read_b128 v[204:207], v245 offset:35840
	ds_read_b128 v[220:223], v245 offset:36864
	ds_read_b128 v[224:227], v245 offset:37888
	ds_read_b128 v[228:231], v245 offset:38912
	ds_read_b128 v[246:249], v245 offset:39936
	s_add_i32 s17, s17, 0x80000
	s_mov_b32 m0, s69
	s_nop 0
	buffer_load_dwordx4 v242, s[24:27], s17 offen lds
	s_mov_b32 m0, s70
	s_nop 0
	buffer_load_dwordx4 v243, s[24:27], s17 offen lds
	s_waitcnt vmcnt(8)
	s_waitcnt lgkmcnt(0)
	s_barrier
	s_setprio 1
	s_waitcnt lgkmcnt(7)
	v_mfma_f32_16x16x32_bf16 v[180:183], v[48:51], v[192:195], v[180:183]
	v_mfma_f32_16x16x32_bf16 v[164:167], v[64:67], v[192:195], v[164:167]
	s_waitcnt lgkmcnt(5)
	v_mfma_f32_16x16x32_bf16 v[148:151], v[48:51], v[200:203], v[148:151]
	v_mfma_f32_16x16x32_bf16 v[140:143], v[64:67], v[200:203], v[140:143]
	s_waitcnt lgkmcnt(3)
	v_mfma_f32_16x16x32_bf16 v[132:135], v[48:51], v[220:223], v[132:135]
	v_mfma_f32_16x16x32_bf16 v[124:127], v[64:67], v[220:223], v[124:127]
	s_waitcnt lgkmcnt(1)
	v_mfma_f32_16x16x32_bf16 v[116:119], v[48:51], v[228:231], v[116:119]
	v_mfma_f32_16x16x32_bf16 v[108:111], v[64:67], v[228:231], v[108:111]
	v_mfma_f32_16x16x32_bf16 v[180:183], v[56:59], v[196:199], v[180:183]
	v_mfma_f32_16x16x32_bf16 v[164:167], v[72:75], v[196:199], v[164:167]
	v_mfma_f32_16x16x32_bf16 v[148:151], v[56:59], v[204:207], v[148:151]
	v_mfma_f32_16x16x32_bf16 v[140:143], v[72:75], v[204:207], v[140:143]
	v_mfma_f32_16x16x32_bf16 v[132:135], v[56:59], v[224:227], v[132:135]
	v_mfma_f32_16x16x32_bf16 v[124:127], v[72:75], v[224:227], v[124:127]
	s_waitcnt lgkmcnt(0)
	v_mfma_f32_16x16x32_bf16 v[116:119], v[56:59], v[246:249], v[116:119]
	v_mfma_f32_16x16x32_bf16 v[108:111], v[72:75], v[246:249], v[108:111]
	s_setprio 0
	s_setprio 1
	v_mfma_f32_16x16x32_bf16 v[172:175], v[152:155], v[192:195], v[172:175]
	v_mfma_f32_16x16x32_bf16 v[156:159], v[168:171], v[192:195], v[156:159]
	v_mfma_f32_16x16x32_bf16 v[144:147], v[152:155], v[200:203], v[144:147]
	v_mfma_f32_16x16x32_bf16 v[136:139], v[168:171], v[200:203], v[136:139]
	v_mfma_f32_16x16x32_bf16 v[128:131], v[152:155], v[220:223], v[128:131]
	v_mfma_f32_16x16x32_bf16 v[120:123], v[168:171], v[220:223], v[120:123]
	v_mfma_f32_16x16x32_bf16 v[112:115], v[152:155], v[228:231], v[112:115]
	v_mfma_f32_16x16x32_bf16 v[104:107], v[168:171], v[228:231], v[104:107]
	v_mfma_f32_16x16x32_bf16 v[172:175], v[160:163], v[196:199], v[172:175]
	v_mfma_f32_16x16x32_bf16 v[156:159], v[176:179], v[196:199], v[156:159]
	v_mfma_f32_16x16x32_bf16 v[144:147], v[160:163], v[204:207], v[144:147]
	v_mfma_f32_16x16x32_bf16 v[136:139], v[176:179], v[204:207], v[136:139]
	v_mfma_f32_16x16x32_bf16 v[128:131], v[160:163], v[224:227], v[128:131]
	v_mfma_f32_16x16x32_bf16 v[120:123], v[176:179], v[224:227], v[120:123]
	v_mfma_f32_16x16x32_bf16 v[112:115], v[160:163], v[246:249], v[112:115]
	v_mfma_f32_16x16x32_bf16 v[104:107], v[176:179], v[246:249], v[104:107]
	s_setprio 0
	s_barrier
	ds_read_b128 v[192:195], v245 offset:49152
	ds_read_b128 v[196:199], v245 offset:50176
	ds_read_b128 v[200:203], v245 offset:51200
	ds_read_b128 v[204:207], v245 offset:52224
	ds_read_b128 v[220:223], v245 offset:53248
	ds_read_b128 v[224:227], v245 offset:54272
	ds_read_b128 v[228:231], v245 offset:55296
	ds_read_b128 v[246:249], v245 offset:56320
	s_or_b32 s17, s16, 0x4000
	s_mov_b32 m0, s73
	s_nop 0
	buffer_load_dwordx4 v242, s[56:59], s17 offen lds
	s_add_i32 s16, s16, 0x84000
	s_mov_b32 m0, s74
	s_nop 0
	buffer_load_dwordx4 v243, s[56:59], s17 offen lds
	s_mov_b32 m0, s77
	s_nop 0
	buffer_load_dwordx4 v242, s[56:59], s16 offen lds
	s_mov_b32 m0, s78
	s_nop 0
	buffer_load_dwordx4 v243, s[56:59], s16 offen lds
	s_mov_b32 m0, s75
	s_nop 0
	buffer_load_dwordx4 v242, s[24:27], s7 offen lds
	s_mov_b32 m0, s76
	s_nop 0
	buffer_load_dwordx4 v243, s[24:27], s7 offen lds
	s_waitcnt vmcnt(8)
	s_waitcnt lgkmcnt(0)
	s_barrier
	s_setprio 1
	s_waitcnt lgkmcnt(7)
	v_mfma_f32_16x16x32_bf16 v[76:79], v[48:51], v[192:195], v[76:79]
	v_mfma_f32_16x16x32_bf16 v[68:71], v[64:67], v[192:195], v[68:71]
	s_waitcnt lgkmcnt(5)
	v_mfma_f32_16x16x32_bf16 v[60:63], v[48:51], v[200:203], v[60:63]
	v_mfma_f32_16x16x32_bf16 v[52:55], v[64:67], v[200:203], v[52:55]
	s_waitcnt lgkmcnt(3)
	v_mfma_f32_16x16x32_bf16 v[44:47], v[48:51], v[220:223], v[44:47]
	v_mfma_f32_16x16x32_bf16 v[36:39], v[64:67], v[220:223], v[36:39]
	s_waitcnt lgkmcnt(1)
	v_mfma_f32_16x16x32_bf16 v[12:15], v[48:51], v[228:231], v[12:15]
	v_mfma_f32_16x16x32_bf16 v[4:7], v[64:67], v[228:231], v[4:7]
	v_mfma_f32_16x16x32_bf16 v[76:79], v[56:59], v[196:199], v[76:79]
	v_mfma_f32_16x16x32_bf16 v[68:71], v[72:75], v[196:199], v[68:71]
	v_mfma_f32_16x16x32_bf16 v[60:63], v[56:59], v[204:207], v[60:63]
	v_mfma_f32_16x16x32_bf16 v[52:55], v[72:75], v[204:207], v[52:55]
	v_mfma_f32_16x16x32_bf16 v[44:47], v[56:59], v[224:227], v[44:47]
	v_mfma_f32_16x16x32_bf16 v[36:39], v[72:75], v[224:227], v[36:39]
	s_waitcnt lgkmcnt(0)
	v_mfma_f32_16x16x32_bf16 v[12:15], v[56:59], v[246:249], v[12:15]
	v_mfma_f32_16x16x32_bf16 v[4:7], v[72:75], v[246:249], v[4:7]
	s_setprio 0
	s_setprio 1
	v_mfma_f32_16x16x32_bf16 v[16:19], v[152:155], v[192:195], v[16:19]
	v_mfma_f32_16x16x32_bf16 v[72:75], v[160:163], v[196:199], v[16:19]
	v_mfma_f32_16x16x32_bf16 v[16:19], v[168:171], v[192:195], v[20:23]
	v_mfma_f32_16x16x32_bf16 v[64:67], v[176:179], v[196:199], v[16:19]
	v_mfma_f32_16x16x32_bf16 v[16:19], v[152:155], v[200:203], v[24:27]
	v_mfma_f32_16x16x32_bf16 v[56:59], v[160:163], v[204:207], v[16:19]
	v_mfma_f32_16x16x32_bf16 v[16:19], v[168:171], v[200:203], v[28:31]
	v_mfma_f32_16x16x32_bf16 v[48:51], v[176:179], v[204:207], v[16:19]
	v_mfma_f32_16x16x32_bf16 v[16:19], v[152:155], v[220:223], v[40:43]
	v_mfma_f32_16x16x32_bf16 v[40:43], v[160:163], v[224:227], v[16:19]
	v_mfma_f32_16x16x32_bf16 v[16:19], v[168:171], v[220:223], v[32:35]
	v_mfma_f32_16x16x32_bf16 v[8:11], v[152:155], v[228:231], v[8:11]
	v_mfma_f32_16x16x32_bf16 v[0:3], v[168:171], v[228:231], v[0:3]
	v_mfma_f32_16x16x32_bf16 v[32:35], v[176:179], v[224:227], v[16:19]
	v_mfma_f32_16x16x32_bf16 v[8:11], v[160:163], v[246:249], v[8:11]
	v_mfma_f32_16x16x32_bf16 v[0:3], v[176:179], v[246:249], v[0:3]
	s_setprio 0
	s_barrier
	s_add_i32 s6, s6, 2
	s_add_i32 s4, s4, 0x8000
	s_add_i32 s5, s5, 0x8000
.LBB0_143:
	v_add_u32_e32 v28, 0x10000, v83
	v_add_u32_e32 v80, 0x14000, v83
	ds_read_b128 v[16:19], v28
	ds_read_b128 v[20:23], v28 offset:1024
	ds_read_b128 v[24:27], v28 offset:2048
	ds_read_b128 v[28:31], v28 offset:3072
	ds_read_b128 v[152:155], v80
	ds_read_b128 v[160:163], v80 offset:1024
	ds_read_b128 v[168:171], v80 offset:2048
	ds_read_b128 v[176:179], v80 offset:3072
	s_add_i32 s7, s4, 0xfff84000
	s_cmp_eq_u32 s6, 28
	s_cselect_b32 s17, s0, s7
	s_cselect_b32 s16, s1, s5
	s_or_b32 s7, s17, 0x4000
	ds_read_b128 v[192:195], v245
	ds_read_b128 v[196:199], v245 offset:1024
	ds_read_b128 v[200:203], v245 offset:2048
	ds_read_b128 v[204:207], v245 offset:3072
	ds_read_b128 v[220:223], v245 offset:4096
	ds_read_b128 v[224:227], v245 offset:5120
	ds_read_b128 v[228:231], v245 offset:6144
	ds_read_b128 v[246:249], v245 offset:7168
	s_mov_b32 m0, s79
	s_nop 0
	buffer_load_dwordx4 v242, s[24:27], s4 offen lds
	s_mov_b32 m0, s83
	s_nop 0
	buffer_load_dwordx4 v243, s[24:27], s4 offen lds
	s_waitcnt vmcnt(8)
	s_waitcnt lgkmcnt(0)
	s_barrier
	s_setprio 1
	s_waitcnt lgkmcnt(7)
	v_mfma_f32_16x16x32_bf16 v[180:183], v[16:19], v[192:195], v[180:183]
	v_mfma_f32_16x16x32_bf16 v[164:167], v[24:27], v[192:195], v[164:167]
	s_waitcnt lgkmcnt(5)
	v_mfma_f32_16x16x32_bf16 v[148:151], v[16:19], v[200:203], v[148:151]
	v_mfma_f32_16x16x32_bf16 v[140:143], v[24:27], v[200:203], v[140:143]
	s_waitcnt lgkmcnt(3)
	v_mfma_f32_16x16x32_bf16 v[132:135], v[16:19], v[220:223], v[132:135]
	v_mfma_f32_16x16x32_bf16 v[124:127], v[24:27], v[220:223], v[124:127]
	s_waitcnt lgkmcnt(1)
	v_mfma_f32_16x16x32_bf16 v[116:119], v[16:19], v[228:231], v[116:119]
	v_mfma_f32_16x16x32_bf16 v[108:111], v[24:27], v[228:231], v[108:111]
	v_mfma_f32_16x16x32_bf16 v[180:183], v[20:23], v[196:199], v[180:183]
	v_mfma_f32_16x16x32_bf16 v[164:167], v[28:31], v[196:199], v[164:167]
	v_mfma_f32_16x16x32_bf16 v[148:151], v[20:23], v[204:207], v[148:151]
	v_mfma_f32_16x16x32_bf16 v[140:143], v[28:31], v[204:207], v[140:143]
	v_mfma_f32_16x16x32_bf16 v[132:135], v[20:23], v[224:227], v[132:135]
	v_mfma_f32_16x16x32_bf16 v[124:127], v[28:31], v[224:227], v[124:127]
	s_waitcnt lgkmcnt(0)
	v_mfma_f32_16x16x32_bf16 v[116:119], v[20:23], v[246:249], v[116:119]
	v_mfma_f32_16x16x32_bf16 v[108:111], v[28:31], v[246:249], v[108:111]
	s_setprio 0
	s_setprio 1
	v_mfma_f32_16x16x32_bf16 v[172:175], v[152:155], v[192:195], v[172:175]
	v_mfma_f32_16x16x32_bf16 v[156:159], v[168:171], v[192:195], v[156:159]
	v_mfma_f32_16x16x32_bf16 v[144:147], v[152:155], v[200:203], v[144:147]
	v_mfma_f32_16x16x32_bf16 v[136:139], v[168:171], v[200:203], v[136:139]
	v_mfma_f32_16x16x32_bf16 v[128:131], v[152:155], v[220:223], v[128:131]
	v_mfma_f32_16x16x32_bf16 v[120:123], v[168:171], v[220:223], v[120:123]
	v_mfma_f32_16x16x32_bf16 v[112:115], v[152:155], v[228:231], v[112:115]
	v_mfma_f32_16x16x32_bf16 v[104:107], v[168:171], v[228:231], v[104:107]
	v_mfma_f32_16x16x32_bf16 v[172:175], v[160:163], v[196:199], v[172:175]
	v_mfma_f32_16x16x32_bf16 v[156:159], v[176:179], v[196:199], v[156:159]
	v_mfma_f32_16x16x32_bf16 v[144:147], v[160:163], v[204:207], v[144:147]
	v_mfma_f32_16x16x32_bf16 v[136:139], v[176:179], v[204:207], v[136:139]
	v_mfma_f32_16x16x32_bf16 v[128:131], v[160:163], v[224:227], v[128:131]
	v_mfma_f32_16x16x32_bf16 v[120:123], v[176:179], v[224:227], v[120:123]
	v_mfma_f32_16x16x32_bf16 v[112:115], v[160:163], v[246:249], v[112:115]
	v_mfma_f32_16x16x32_bf16 v[104:107], v[176:179], v[246:249], v[104:107]
	s_setprio 0
	s_barrier
	ds_read_b128 v[192:195], v245 offset:16384
	ds_read_b128 v[196:199], v245 offset:17408
	ds_read_b128 v[200:203], v245 offset:18432
	ds_read_b128 v[204:207], v245 offset:19456
	ds_read_b128 v[220:223], v245 offset:20480
	ds_read_b128 v[224:227], v245 offset:21504
	ds_read_b128 v[228:231], v245 offset:22528
	ds_read_b128 v[246:249], v245 offset:23552
	s_mov_b32 m0, s51
	s_nop 0
	buffer_load_dwordx4 v242, s[56:59], s16 offen lds
	s_add_i32 s18, s16, 0x80000
	s_mov_b32 m0, s52
	s_nop 0
	buffer_load_dwordx4 v243, s[56:59], s16 offen lds
	s_mov_b32 m0, s53
	s_nop 0
	buffer_load_dwordx4 v242, s[56:59], s18 offen lds
	s_mov_b32 m0, s55
	s_nop 0
	buffer_load_dwordx4 v243, s[56:59], s18 offen lds
	s_mov_b32 m0, s31
	s_nop 0
	buffer_load_dwordx4 v242, s[24:27], s17 offen lds
	s_mov_b32 m0, s68
	s_nop 0
	buffer_load_dwordx4 v243, s[24:27], s17 offen lds
	s_waitcnt vmcnt(8)
	s_waitcnt lgkmcnt(0)
	s_barrier
	s_setprio 1
	s_waitcnt lgkmcnt(7)
	v_mfma_f32_16x16x32_bf16 v[76:79], v[16:19], v[192:195], v[76:79]
	v_mfma_f32_16x16x32_bf16 v[68:71], v[24:27], v[192:195], v[68:71]
	s_waitcnt lgkmcnt(5)
	v_mfma_f32_16x16x32_bf16 v[60:63], v[16:19], v[200:203], v[60:63]
	v_mfma_f32_16x16x32_bf16 v[52:55], v[24:27], v[200:203], v[52:55]
	s_waitcnt lgkmcnt(3)
	v_mfma_f32_16x16x32_bf16 v[44:47], v[16:19], v[220:223], v[44:47]
	v_mfma_f32_16x16x32_bf16 v[36:39], v[24:27], v[220:223], v[36:39]
	s_waitcnt lgkmcnt(1)
	v_mfma_f32_16x16x32_bf16 v[12:15], v[16:19], v[228:231], v[12:15]
	v_mfma_f32_16x16x32_bf16 v[4:7], v[24:27], v[228:231], v[4:7]
	v_mfma_f32_16x16x32_bf16 v[76:79], v[20:23], v[196:199], v[76:79]
	v_mfma_f32_16x16x32_bf16 v[68:71], v[28:31], v[196:199], v[68:71]
	v_mfma_f32_16x16x32_bf16 v[60:63], v[20:23], v[204:207], v[60:63]
	v_mfma_f32_16x16x32_bf16 v[52:55], v[28:31], v[204:207], v[52:55]
	v_mfma_f32_16x16x32_bf16 v[44:47], v[20:23], v[224:227], v[44:47]
	v_mfma_f32_16x16x32_bf16 v[36:39], v[28:31], v[224:227], v[36:39]
	s_waitcnt lgkmcnt(0)
	v_mfma_f32_16x16x32_bf16 v[12:15], v[20:23], v[246:249], v[12:15]
	v_mfma_f32_16x16x32_bf16 v[4:7], v[28:31], v[246:249], v[4:7]
	s_setprio 0
	s_setprio 1
	v_mfma_f32_16x16x32_bf16 v[40:43], v[152:155], v[220:223], v[40:43]
	v_mfma_f32_16x16x32_bf16 v[32:35], v[168:171], v[220:223], v[32:35]
	v_mfma_f32_16x16x32_bf16 v[8:11], v[152:155], v[228:231], v[8:11]
	v_mfma_f32_16x16x32_bf16 v[0:3], v[168:171], v[228:231], v[0:3]
	v_mfma_f32_16x16x32_bf16 v[16:19], v[152:155], v[192:195], v[72:75]
	v_mfma_f32_16x16x32_bf16 v[20:23], v[168:171], v[192:195], v[64:67]
	v_mfma_f32_16x16x32_bf16 v[24:27], v[152:155], v[200:203], v[56:59]
	v_mfma_f32_16x16x32_bf16 v[28:31], v[168:171], v[200:203], v[48:51]
	v_mfma_f32_16x16x32_bf16 v[40:43], v[160:163], v[224:227], v[40:43]
	v_mfma_f32_16x16x32_bf16 v[32:35], v[176:179], v[224:227], v[32:35]
	v_mfma_f32_16x16x32_bf16 v[8:11], v[160:163], v[246:249], v[8:11]
	v_mfma_f32_16x16x32_bf16 v[0:3], v[176:179], v[246:249], v[0:3]
	v_mfma_f32_16x16x32_bf16 v[16:19], v[160:163], v[196:199], v[16:19]
	v_mfma_f32_16x16x32_bf16 v[20:23], v[176:179], v[196:199], v[20:23]
	v_mfma_f32_16x16x32_bf16 v[24:27], v[160:163], v[204:207], v[24:27]
	v_mfma_f32_16x16x32_bf16 v[28:31], v[176:179], v[204:207], v[28:31]
	s_setprio 0
	s_barrier
	v_add_u32_e32 v72, 0x18000, v83
	v_add_u32_e32 v80, 0x1c000, v83
	ds_read_b128 v[48:51], v72
	ds_read_b128 v[56:59], v72 offset:1024
	ds_read_b128 v[64:67], v72 offset:2048
	ds_read_b128 v[72:75], v72 offset:3072
	ds_read_b128 v[152:155], v80
	ds_read_b128 v[160:163], v80 offset:1024
	ds_read_b128 v[168:171], v80 offset:2048
	ds_read_b128 v[176:179], v80 offset:3072
	ds_read_b128 v[192:195], v245 offset:32768
	ds_read_b128 v[196:199], v245 offset:33792
	ds_read_b128 v[200:203], v245 offset:34816
	ds_read_b128 v[204:207], v245 offset:35840
	ds_read_b128 v[220:223], v245 offset:36864
	ds_read_b128 v[224:227], v245 offset:37888
	ds_read_b128 v[228:231], v245 offset:38912
	ds_read_b128 v[246:249], v245 offset:39936
	s_add_i32 s17, s17, 0x80000
	s_mov_b32 m0, s69
	s_nop 0
	buffer_load_dwordx4 v242, s[24:27], s17 offen lds
	s_mov_b32 m0, s70
	s_nop 0
	buffer_load_dwordx4 v243, s[24:27], s17 offen lds
	s_waitcnt vmcnt(8)
	s_waitcnt lgkmcnt(0)
	s_barrier
	s_setprio 1
	s_waitcnt lgkmcnt(7)
	v_mfma_f32_16x16x32_bf16 v[180:183], v[48:51], v[192:195], v[180:183]
	v_mfma_f32_16x16x32_bf16 v[164:167], v[64:67], v[192:195], v[164:167]
	s_waitcnt lgkmcnt(5)
	v_mfma_f32_16x16x32_bf16 v[148:151], v[48:51], v[200:203], v[148:151]
	v_mfma_f32_16x16x32_bf16 v[140:143], v[64:67], v[200:203], v[140:143]
	s_waitcnt lgkmcnt(3)
	v_mfma_f32_16x16x32_bf16 v[132:135], v[48:51], v[220:223], v[132:135]
	v_mfma_f32_16x16x32_bf16 v[124:127], v[64:67], v[220:223], v[124:127]
	s_waitcnt lgkmcnt(1)
	v_mfma_f32_16x16x32_bf16 v[116:119], v[48:51], v[228:231], v[116:119]
	v_mfma_f32_16x16x32_bf16 v[108:111], v[64:67], v[228:231], v[108:111]
	v_mfma_f32_16x16x32_bf16 v[180:183], v[56:59], v[196:199], v[180:183]
	v_mfma_f32_16x16x32_bf16 v[164:167], v[72:75], v[196:199], v[164:167]
	v_mfma_f32_16x16x32_bf16 v[148:151], v[56:59], v[204:207], v[148:151]
	v_mfma_f32_16x16x32_bf16 v[140:143], v[72:75], v[204:207], v[140:143]
	v_mfma_f32_16x16x32_bf16 v[132:135], v[56:59], v[224:227], v[132:135]
	v_mfma_f32_16x16x32_bf16 v[124:127], v[72:75], v[224:227], v[124:127]
	s_waitcnt lgkmcnt(0)
	v_mfma_f32_16x16x32_bf16 v[116:119], v[56:59], v[246:249], v[116:119]
	v_mfma_f32_16x16x32_bf16 v[108:111], v[72:75], v[246:249], v[108:111]
	s_setprio 0
	s_setprio 1
	v_mfma_f32_16x16x32_bf16 v[172:175], v[152:155], v[192:195], v[172:175]
	v_mfma_f32_16x16x32_bf16 v[156:159], v[168:171], v[192:195], v[156:159]
	v_mfma_f32_16x16x32_bf16 v[144:147], v[152:155], v[200:203], v[144:147]
	v_mfma_f32_16x16x32_bf16 v[136:139], v[168:171], v[200:203], v[136:139]
	v_mfma_f32_16x16x32_bf16 v[128:131], v[152:155], v[220:223], v[128:131]
	v_mfma_f32_16x16x32_bf16 v[120:123], v[168:171], v[220:223], v[120:123]
	v_mfma_f32_16x16x32_bf16 v[112:115], v[152:155], v[228:231], v[112:115]
	v_mfma_f32_16x16x32_bf16 v[104:107], v[168:171], v[228:231], v[104:107]
	v_mfma_f32_16x16x32_bf16 v[172:175], v[160:163], v[196:199], v[172:175]
	v_mfma_f32_16x16x32_bf16 v[156:159], v[176:179], v[196:199], v[156:159]
	v_mfma_f32_16x16x32_bf16 v[144:147], v[160:163], v[204:207], v[144:147]
	v_mfma_f32_16x16x32_bf16 v[136:139], v[176:179], v[204:207], v[136:139]
	v_mfma_f32_16x16x32_bf16 v[128:131], v[160:163], v[224:227], v[128:131]
	v_mfma_f32_16x16x32_bf16 v[120:123], v[176:179], v[224:227], v[120:123]
	v_mfma_f32_16x16x32_bf16 v[112:115], v[160:163], v[246:249], v[112:115]
	v_mfma_f32_16x16x32_bf16 v[104:107], v[176:179], v[246:249], v[104:107]
	s_setprio 0
	s_barrier
	ds_read_b128 v[192:195], v245 offset:49152
	ds_read_b128 v[196:199], v245 offset:50176
	ds_read_b128 v[200:203], v245 offset:51200
	ds_read_b128 v[204:207], v245 offset:52224
	ds_read_b128 v[220:223], v245 offset:53248
	ds_read_b128 v[224:227], v245 offset:54272
	ds_read_b128 v[228:231], v245 offset:55296
	ds_read_b128 v[246:249], v245 offset:56320
	s_or_b32 s17, s16, 0x4000
	s_mov_b32 m0, s73
	s_nop 0
	buffer_load_dwordx4 v242, s[56:59], s17 offen lds
	s_add_i32 s16, s16, 0x84000
	s_mov_b32 m0, s74
	s_nop 0
	buffer_load_dwordx4 v243, s[56:59], s17 offen lds
	s_mov_b32 m0, s77
	s_nop 0
	buffer_load_dwordx4 v242, s[56:59], s16 offen lds
	s_mov_b32 m0, s78
	s_nop 0
	buffer_load_dwordx4 v243, s[56:59], s16 offen lds
	s_mov_b32 m0, s75
	s_nop 0
	buffer_load_dwordx4 v242, s[24:27], s7 offen lds
	s_mov_b32 m0, s76
	s_nop 0
	buffer_load_dwordx4 v243, s[24:27], s7 offen lds
	s_waitcnt vmcnt(8)
	s_waitcnt lgkmcnt(0)
	s_barrier
	s_setprio 1
	s_waitcnt lgkmcnt(7)
	v_mfma_f32_16x16x32_bf16 v[76:79], v[48:51], v[192:195], v[76:79]
	v_mfma_f32_16x16x32_bf16 v[68:71], v[64:67], v[192:195], v[68:71]
	s_waitcnt lgkmcnt(5)
	v_mfma_f32_16x16x32_bf16 v[60:63], v[48:51], v[200:203], v[60:63]
	v_mfma_f32_16x16x32_bf16 v[52:55], v[64:67], v[200:203], v[52:55]
	s_waitcnt lgkmcnt(3)
	v_mfma_f32_16x16x32_bf16 v[44:47], v[48:51], v[220:223], v[44:47]
	v_mfma_f32_16x16x32_bf16 v[36:39], v[64:67], v[220:223], v[36:39]
	s_waitcnt lgkmcnt(1)
	v_mfma_f32_16x16x32_bf16 v[12:15], v[48:51], v[228:231], v[12:15]
	v_mfma_f32_16x16x32_bf16 v[4:7], v[64:67], v[228:231], v[4:7]
	v_mfma_f32_16x16x32_bf16 v[76:79], v[56:59], v[196:199], v[76:79]
	v_mfma_f32_16x16x32_bf16 v[68:71], v[72:75], v[196:199], v[68:71]
	v_mfma_f32_16x16x32_bf16 v[60:63], v[56:59], v[204:207], v[60:63]
	v_mfma_f32_16x16x32_bf16 v[52:55], v[72:75], v[204:207], v[52:55]
	v_mfma_f32_16x16x32_bf16 v[44:47], v[56:59], v[224:227], v[44:47]
	v_mfma_f32_16x16x32_bf16 v[36:39], v[72:75], v[224:227], v[36:39]
	s_waitcnt lgkmcnt(0)
	v_mfma_f32_16x16x32_bf16 v[12:15], v[56:59], v[246:249], v[12:15]
	v_mfma_f32_16x16x32_bf16 v[4:7], v[72:75], v[246:249], v[4:7]
	s_setprio 0
	s_setprio 1
	v_mfma_f32_16x16x32_bf16 v[16:19], v[152:155], v[192:195], v[16:19]
	v_mfma_f32_16x16x32_bf16 v[72:75], v[160:163], v[196:199], v[16:19]
	v_mfma_f32_16x16x32_bf16 v[16:19], v[168:171], v[192:195], v[20:23]
	v_mfma_f32_16x16x32_bf16 v[64:67], v[176:179], v[196:199], v[16:19]
	v_mfma_f32_16x16x32_bf16 v[16:19], v[152:155], v[200:203], v[24:27]
	v_mfma_f32_16x16x32_bf16 v[56:59], v[160:163], v[204:207], v[16:19]
	v_mfma_f32_16x16x32_bf16 v[16:19], v[168:171], v[200:203], v[28:31]
	v_mfma_f32_16x16x32_bf16 v[48:51], v[176:179], v[204:207], v[16:19]
	v_mfma_f32_16x16x32_bf16 v[16:19], v[152:155], v[220:223], v[40:43]
	v_mfma_f32_16x16x32_bf16 v[40:43], v[160:163], v[224:227], v[16:19]
	v_mfma_f32_16x16x32_bf16 v[16:19], v[168:171], v[220:223], v[32:35]
	v_mfma_f32_16x16x32_bf16 v[8:11], v[152:155], v[228:231], v[8:11]
	v_mfma_f32_16x16x32_bf16 v[0:3], v[168:171], v[228:231], v[0:3]
	v_mfma_f32_16x16x32_bf16 v[32:35], v[176:179], v[224:227], v[16:19]
	v_mfma_f32_16x16x32_bf16 v[8:11], v[160:163], v[246:249], v[8:11]
	v_mfma_f32_16x16x32_bf16 v[0:3], v[176:179], v[246:249], v[0:3]
	s_setprio 0
	s_barrier
	s_add_i32 s6, s6, 2
	s_add_i32 s4, s4, 0x8000
	s_add_i32 s5, s5, 0x8000
	s_cmp_gt_u32 s6, 29
	s_cbranch_scc0 .LBB0_143
	s_and_b64 vcc, exec, s[10:11]
	s_cbranch_vccz .LBB0_146
	s_barrier

.LBB0_594:
	v_add_u32_e32 v80, 0x10000, v226
	ds_read_b128 v[152:155], v80
	ds_read_b128 v[156:159], v80 offset:1024
	ds_read_b128 v[160:163], v80 offset:2048
	ds_read_b128 v[164:167], v80 offset:3072
	v_add_u32_e32 v80, 0x14000, v226
	ds_read_b128 v[168:171], v80
	ds_read_b128 v[172:175], v80 offset:1024
	ds_read_b128 v[176:179], v80 offset:2048
	ds_read_b128 v[180:183], v80 offset:3072
	s_add_i32 s97, s96, s39
	s_add_i32 s94, s97, 0x8000
	s_add_i32 s95, s93, s39
	s_cmp_eq_u32 s39, 0x78000
	s_cselect_b32 s36, vcc_lo, s94
	s_cselect_b32 s95, vcc_hi, s95
	s_or_b32 s94, s36, 0x4000
	ds_read_b128 v[184:187], v227
	ds_read_b128 v[188:191], v227 offset:1024
	ds_read_b128 v[192:195], v227 offset:2048
	ds_read_b128 v[196:199], v227 offset:3072
	ds_read_b128 v[200:203], v227 offset:4096
	ds_read_b128 v[204:207], v227 offset:5120
	ds_read_b128 v[228:231], v227 offset:6144
	ds_read_b128 v[240:243], v227 offset:7168
	s_add_i32 s97, s97, 0x84000
	s_mov_b32 m0, s85
	s_nop 0
	buffer_load_dwordx4 v224, s[60:63], s97 offen lds
	s_mov_b32 m0, s86
	s_nop 0
	buffer_load_dwordx4 v225, s[60:63], s97 offen lds
	s_waitcnt vmcnt(8)
	s_waitcnt lgkmcnt(0)
	s_barrier
	s_setprio 1
	s_waitcnt lgkmcnt(7)
	v_mfma_f32_16x16x32_bf16 v[148:151], v[152:155], v[184:187], v[148:151]
	v_mfma_f32_16x16x32_bf16 v[144:147], v[160:163], v[184:187], v[144:147]
	s_waitcnt lgkmcnt(5)
	v_mfma_f32_16x16x32_bf16 v[132:135], v[152:155], v[192:195], v[132:135]
	v_mfma_f32_16x16x32_bf16 v[128:131], v[160:163], v[192:195], v[128:131]
	s_waitcnt lgkmcnt(3)
	v_mfma_f32_16x16x32_bf16 v[116:119], v[152:155], v[200:203], v[116:119]
	v_mfma_f32_16x16x32_bf16 v[112:115], v[160:163], v[200:203], v[112:115]
	s_waitcnt lgkmcnt(1)
	v_mfma_f32_16x16x32_bf16 v[76:79], v[152:155], v[228:231], v[76:79]
	v_mfma_f32_16x16x32_bf16 v[72:75], v[160:163], v[228:231], v[72:75]
	v_mfma_f32_16x16x32_bf16 v[148:151], v[156:159], v[188:191], v[148:151]
	v_mfma_f32_16x16x32_bf16 v[144:147], v[164:167], v[188:191], v[144:147]
	v_mfma_f32_16x16x32_bf16 v[132:135], v[156:159], v[196:199], v[132:135]
	v_mfma_f32_16x16x32_bf16 v[128:131], v[164:167], v[196:199], v[128:131]
	v_mfma_f32_16x16x32_bf16 v[116:119], v[156:159], v[204:207], v[116:119]
	v_mfma_f32_16x16x32_bf16 v[112:115], v[164:167], v[204:207], v[112:115]
	s_waitcnt lgkmcnt(0)
	v_mfma_f32_16x16x32_bf16 v[76:79], v[156:159], v[240:243], v[76:79]
	v_mfma_f32_16x16x32_bf16 v[72:75], v[164:167], v[240:243], v[72:75]
	s_setprio 0
	s_setprio 1
	v_mfma_f32_16x16x32_bf16 v[140:143], v[168:171], v[184:187], v[140:143]
	v_mfma_f32_16x16x32_bf16 v[136:139], v[176:179], v[184:187], v[136:139]
	v_mfma_f32_16x16x32_bf16 v[124:127], v[168:171], v[192:195], v[124:127]
	v_mfma_f32_16x16x32_bf16 v[120:123], v[176:179], v[192:195], v[120:123]
	v_mfma_f32_16x16x32_bf16 v[108:111], v[168:171], v[200:203], v[108:111]
	v_mfma_f32_16x16x32_bf16 v[104:107], v[176:179], v[200:203], v[104:107]
	v_mfma_f32_16x16x32_bf16 v[68:71], v[168:171], v[228:231], v[68:71]
	v_mfma_f32_16x16x32_bf16 v[64:67], v[176:179], v[228:231], v[64:67]
	v_mfma_f32_16x16x32_bf16 v[140:143], v[172:175], v[188:191], v[140:143]
	v_mfma_f32_16x16x32_bf16 v[136:139], v[180:183], v[188:191], v[136:139]
	v_mfma_f32_16x16x32_bf16 v[124:127], v[172:175], v[196:199], v[124:127]
	v_mfma_f32_16x16x32_bf16 v[120:123], v[180:183], v[196:199], v[120:123]
	v_mfma_f32_16x16x32_bf16 v[108:111], v[172:175], v[204:207], v[108:111]
	v_mfma_f32_16x16x32_bf16 v[104:107], v[180:183], v[204:207], v[104:107]
	v_mfma_f32_16x16x32_bf16 v[68:71], v[172:175], v[240:243], v[68:71]
	v_mfma_f32_16x16x32_bf16 v[64:67], v[180:183], v[240:243], v[64:67]
	s_setprio 0
	s_barrier
	ds_read_b128 v[184:187], v227 offset:16384
	ds_read_b128 v[188:191], v227 offset:17408
	ds_read_b128 v[192:195], v227 offset:18432
	ds_read_b128 v[196:199], v227 offset:19456
	ds_read_b128 v[200:203], v227 offset:20480
	ds_read_b128 v[204:207], v227 offset:21504
	ds_read_b128 v[228:231], v227 offset:22528
	ds_read_b128 v[240:243], v227 offset:23552
	s_mov_b32 m0, s34
	s_nop 0
	buffer_load_dwordx4 v224, s[48:51], s95 offen lds
	s_add_i32 s97, s95, 0x80000
	s_mov_b32 m0, s55
	s_nop 0
	buffer_load_dwordx4 v225, s[48:51], s95 offen lds
	s_mov_b32 m0, s72
	s_nop 0
	buffer_load_dwordx4 v224, s[48:51], s97 offen lds
	s_mov_b32 m0, s73
	s_nop 0
	buffer_load_dwordx4 v225, s[48:51], s97 offen lds
	s_mov_b32 m0, s31
	s_nop 0
	buffer_load_dwordx4 v224, s[60:63], s36 offen lds
	s_mov_b32 m0, s74
	s_nop 0
	buffer_load_dwordx4 v225, s[60:63], s36 offen lds
	s_waitcnt vmcnt(8)
	s_waitcnt lgkmcnt(0)
	s_barrier
	s_setprio 1
	s_waitcnt lgkmcnt(7)
	v_mfma_f32_16x16x32_bf16 v[60:63], v[152:155], v[184:187], v[60:63]
	v_mfma_f32_16x16x32_bf16 v[56:59], v[160:163], v[184:187], v[56:59]
	s_waitcnt lgkmcnt(5)
	v_mfma_f32_16x16x32_bf16 v[44:47], v[152:155], v[192:195], v[44:47]
	v_mfma_f32_16x16x32_bf16 v[40:43], v[160:163], v[192:195], v[40:43]
	s_waitcnt lgkmcnt(3)
	v_mfma_f32_16x16x32_bf16 v[28:31], v[152:155], v[200:203], v[28:31]
	v_mfma_f32_16x16x32_bf16 v[24:27], v[160:163], v[200:203], v[24:27]
	s_waitcnt lgkmcnt(1)
	v_mfma_f32_16x16x32_bf16 v[12:15], v[152:155], v[228:231], v[12:15]
	v_mfma_f32_16x16x32_bf16 v[8:11], v[160:163], v[228:231], v[8:11]
	v_mfma_f32_16x16x32_bf16 v[60:63], v[156:159], v[188:191], v[60:63]
	v_mfma_f32_16x16x32_bf16 v[56:59], v[164:167], v[188:191], v[56:59]
	v_mfma_f32_16x16x32_bf16 v[44:47], v[156:159], v[196:199], v[44:47]
	v_mfma_f32_16x16x32_bf16 v[40:43], v[164:167], v[196:199], v[40:43]
	v_mfma_f32_16x16x32_bf16 v[28:31], v[156:159], v[204:207], v[28:31]
	v_mfma_f32_16x16x32_bf16 v[24:27], v[164:167], v[204:207], v[24:27]
	s_waitcnt lgkmcnt(0)
	v_mfma_f32_16x16x32_bf16 v[12:15], v[156:159], v[240:243], v[12:15]
	v_mfma_f32_16x16x32_bf16 v[8:11], v[164:167], v[240:243], v[8:11]
	s_setprio 0
	s_setprio 1
	v_mfma_f32_16x16x32_bf16 v[52:55], v[168:171], v[184:187], v[52:55]
	v_mfma_f32_16x16x32_bf16 v[48:51], v[176:179], v[184:187], v[48:51]
	v_mfma_f32_16x16x32_bf16 v[36:39], v[168:171], v[192:195], v[36:39]
	v_mfma_f32_16x16x32_bf16 v[32:35], v[176:179], v[192:195], v[32:35]
	v_mfma_f32_16x16x32_bf16 v[20:23], v[168:171], v[200:203], v[20:23]
	v_mfma_f32_16x16x32_bf16 v[16:19], v[176:179], v[200:203], v[16:19]
	v_mfma_f32_16x16x32_bf16 v[4:7], v[168:171], v[228:231], v[4:7]
	v_mfma_f32_16x16x32_bf16 v[0:3], v[176:179], v[228:231], v[0:3]
	v_mfma_f32_16x16x32_bf16 v[52:55], v[172:175], v[188:191], v[52:55]
	v_mfma_f32_16x16x32_bf16 v[48:51], v[180:183], v[188:191], v[48:51]
	v_mfma_f32_16x16x32_bf16 v[36:39], v[172:175], v[196:199], v[36:39]
	v_mfma_f32_16x16x32_bf16 v[32:35], v[180:183], v[196:199], v[32:35]
	v_mfma_f32_16x16x32_bf16 v[20:23], v[172:175], v[204:207], v[20:23]
	v_mfma_f32_16x16x32_bf16 v[16:19], v[180:183], v[204:207], v[16:19]
	v_mfma_f32_16x16x32_bf16 v[4:7], v[172:175], v[240:243], v[4:7]
	v_mfma_f32_16x16x32_bf16 v[0:3], v[180:183], v[240:243], v[0:3]
	s_setprio 0
	s_barrier
	v_add_u32_e32 v80, 0x18000, v226
	ds_read_b128 v[152:155], v80
	ds_read_b128 v[156:159], v80 offset:1024
	ds_read_b128 v[160:163], v80 offset:2048
	ds_read_b128 v[164:167], v80 offset:3072
	v_add_u32_e32 v80, 0x1c000, v226
	ds_read_b128 v[168:171], v80
	ds_read_b128 v[172:175], v80 offset:1024
	ds_read_b128 v[176:179], v80 offset:2048
	ds_read_b128 v[180:183], v80 offset:3072
	ds_read_b128 v[184:187], v227 offset:32768
	ds_read_b128 v[188:191], v227 offset:33792
	ds_read_b128 v[192:195], v227 offset:34816
	ds_read_b128 v[196:199], v227 offset:35840
	ds_read_b128 v[200:203], v227 offset:36864
	ds_read_b128 v[204:207], v227 offset:37888
	ds_read_b128 v[228:231], v227 offset:38912
	ds_read_b128 v[240:243], v227 offset:39936
	s_add_i32 s36, s36, 0x80000
	s_mov_b32 m0, s75
	s_nop 0
	buffer_load_dwordx4 v224, s[60:63], s36 offen lds
	s_mov_b32 m0, s76
	s_nop 0
	buffer_load_dwordx4 v225, s[60:63], s36 offen lds
	s_waitcnt vmcnt(8)
	s_waitcnt lgkmcnt(0)
	s_barrier
	s_setprio 1
	s_waitcnt lgkmcnt(7)
	v_mfma_f32_16x16x32_bf16 v[148:151], v[152:155], v[184:187], v[148:151]
	v_mfma_f32_16x16x32_bf16 v[144:147], v[160:163], v[184:187], v[144:147]
	s_waitcnt lgkmcnt(5)
	v_mfma_f32_16x16x32_bf16 v[132:135], v[152:155], v[192:195], v[132:135]
	v_mfma_f32_16x16x32_bf16 v[128:131], v[160:163], v[192:195], v[128:131]
	s_waitcnt lgkmcnt(3)
	v_mfma_f32_16x16x32_bf16 v[116:119], v[152:155], v[200:203], v[116:119]
	v_mfma_f32_16x16x32_bf16 v[112:115], v[160:163], v[200:203], v[112:115]
	s_waitcnt lgkmcnt(1)
	v_mfma_f32_16x16x32_bf16 v[76:79], v[152:155], v[228:231], v[76:79]
	v_mfma_f32_16x16x32_bf16 v[72:75], v[160:163], v[228:231], v[72:75]
	v_mfma_f32_16x16x32_bf16 v[148:151], v[156:159], v[188:191], v[148:151]
	v_mfma_f32_16x16x32_bf16 v[144:147], v[164:167], v[188:191], v[144:147]
	v_mfma_f32_16x16x32_bf16 v[132:135], v[156:159], v[196:199], v[132:135]
	v_mfma_f32_16x16x32_bf16 v[128:131], v[164:167], v[196:199], v[128:131]
	v_mfma_f32_16x16x32_bf16 v[116:119], v[156:159], v[204:207], v[116:119]
	v_mfma_f32_16x16x32_bf16 v[112:115], v[164:167], v[204:207], v[112:115]
	s_waitcnt lgkmcnt(0)
	v_mfma_f32_16x16x32_bf16 v[76:79], v[156:159], v[240:243], v[76:79]
	v_mfma_f32_16x16x32_bf16 v[72:75], v[164:167], v[240:243], v[72:75]
	s_setprio 0
	s_setprio 1
	v_mfma_f32_16x16x32_bf16 v[140:143], v[168:171], v[184:187], v[140:143]
	v_mfma_f32_16x16x32_bf16 v[136:139], v[176:179], v[184:187], v[136:139]
	v_mfma_f32_16x16x32_bf16 v[124:127], v[168:171], v[192:195], v[124:127]
	v_mfma_f32_16x16x32_bf16 v[120:123], v[176:179], v[192:195], v[120:123]
	v_mfma_f32_16x16x32_bf16 v[108:111], v[168:171], v[200:203], v[108:111]
	v_mfma_f32_16x16x32_bf16 v[104:107], v[176:179], v[200:203], v[104:107]
	v_mfma_f32_16x16x32_bf16 v[68:71], v[168:171], v[228:231], v[68:71]
	v_mfma_f32_16x16x32_bf16 v[64:67], v[176:179], v[228:231], v[64:67]
	v_mfma_f32_16x16x32_bf16 v[140:143], v[172:175], v[188:191], v[140:143]
	v_mfma_f32_16x16x32_bf16 v[136:139], v[180:183], v[188:191], v[136:139]
	v_mfma_f32_16x16x32_bf16 v[124:127], v[172:175], v[196:199], v[124:127]
	v_mfma_f32_16x16x32_bf16 v[120:123], v[180:183], v[196:199], v[120:123]
	v_mfma_f32_16x16x32_bf16 v[108:111], v[172:175], v[204:207], v[108:111]
	v_mfma_f32_16x16x32_bf16 v[104:107], v[180:183], v[204:207], v[104:107]
	v_mfma_f32_16x16x32_bf16 v[68:71], v[172:175], v[240:243], v[68:71]
	v_mfma_f32_16x16x32_bf16 v[64:67], v[180:183], v[240:243], v[64:67]
	s_setprio 0
	s_barrier
	ds_read_b128 v[184:187], v227 offset:49152
	ds_read_b128 v[188:191], v227 offset:50176
	ds_read_b128 v[192:195], v227 offset:51200
	ds_read_b128 v[196:199], v227 offset:52224
	ds_read_b128 v[200:203], v227 offset:53248
	ds_read_b128 v[204:207], v227 offset:54272
	ds_read_b128 v[228:231], v227 offset:55296
	ds_read_b128 v[240:243], v227 offset:56320
	s_or_b32 s36, s95, 0x4000
	s_mov_b32 m0, s77
	s_nop 0
	buffer_load_dwordx4 v224, s[48:51], s36 offen lds
	s_mov_b32 m0, s78
	s_nop 0
	buffer_load_dwordx4 v225, s[48:51], s36 offen lds
	s_add_i32 s36, s95, 0x84000
	s_mov_b32 m0, s83
	s_nop 0
	buffer_load_dwordx4 v224, s[48:51], s36 offen lds
	s_mov_b32 m0, s84
	s_nop 0
	buffer_load_dwordx4 v225, s[48:51], s36 offen lds
	s_mov_b32 m0, s79
	s_nop 0
	buffer_load_dwordx4 v224, s[60:63], s94 offen lds
	s_mov_b32 m0, s82
	s_nop 0
	buffer_load_dwordx4 v225, s[60:63], s94 offen lds
	s_waitcnt vmcnt(8)
	s_waitcnt lgkmcnt(0)
	s_barrier
	s_setprio 1
	s_waitcnt lgkmcnt(7)
	v_mfma_f32_16x16x32_bf16 v[60:63], v[152:155], v[184:187], v[60:63]
	v_mfma_f32_16x16x32_bf16 v[56:59], v[160:163], v[184:187], v[56:59]
	s_waitcnt lgkmcnt(5)
	v_mfma_f32_16x16x32_bf16 v[44:47], v[152:155], v[192:195], v[44:47]
	v_mfma_f32_16x16x32_bf16 v[40:43], v[160:163], v[192:195], v[40:43]
	s_waitcnt lgkmcnt(3)
	v_mfma_f32_16x16x32_bf16 v[28:31], v[152:155], v[200:203], v[28:31]
	v_mfma_f32_16x16x32_bf16 v[24:27], v[160:163], v[200:203], v[24:27]
	s_waitcnt lgkmcnt(1)
	v_mfma_f32_16x16x32_bf16 v[12:15], v[152:155], v[228:231], v[12:15]
	v_mfma_f32_16x16x32_bf16 v[8:11], v[160:163], v[228:231], v[8:11]
	v_mfma_f32_16x16x32_bf16 v[60:63], v[156:159], v[188:191], v[60:63]
	v_mfma_f32_16x16x32_bf16 v[56:59], v[164:167], v[188:191], v[56:59]
	v_mfma_f32_16x16x32_bf16 v[44:47], v[156:159], v[196:199], v[44:47]
	v_mfma_f32_16x16x32_bf16 v[40:43], v[164:167], v[196:199], v[40:43]
	v_mfma_f32_16x16x32_bf16 v[28:31], v[156:159], v[204:207], v[28:31]
	v_mfma_f32_16x16x32_bf16 v[24:27], v[164:167], v[204:207], v[24:27]
	s_waitcnt lgkmcnt(0)
	v_mfma_f32_16x16x32_bf16 v[12:15], v[156:159], v[240:243], v[12:15]
	v_mfma_f32_16x16x32_bf16 v[8:11], v[164:167], v[240:243], v[8:11]
	s_setprio 0
	s_setprio 1
	v_mfma_f32_16x16x32_bf16 v[52:55], v[168:171], v[184:187], v[52:55]
	v_mfma_f32_16x16x32_bf16 v[48:51], v[176:179], v[184:187], v[48:51]
	v_mfma_f32_16x16x32_bf16 v[36:39], v[168:171], v[192:195], v[36:39]
	v_mfma_f32_16x16x32_bf16 v[32:35], v[176:179], v[192:195], v[32:35]
	v_mfma_f32_16x16x32_bf16 v[20:23], v[168:171], v[200:203], v[20:23]
	v_mfma_f32_16x16x32_bf16 v[16:19], v[176:179], v[200:203], v[16:19]
	v_mfma_f32_16x16x32_bf16 v[4:7], v[168:171], v[228:231], v[4:7]
	v_mfma_f32_16x16x32_bf16 v[0:3], v[176:179], v[228:231], v[0:3]
	v_mfma_f32_16x16x32_bf16 v[52:55], v[172:175], v[188:191], v[52:55]
	v_mfma_f32_16x16x32_bf16 v[48:51], v[180:183], v[188:191], v[48:51]
	v_mfma_f32_16x16x32_bf16 v[36:39], v[172:175], v[196:199], v[36:39]
	v_mfma_f32_16x16x32_bf16 v[32:35], v[180:183], v[196:199], v[32:35]
	v_mfma_f32_16x16x32_bf16 v[20:23], v[172:175], v[204:207], v[20:23]
	v_mfma_f32_16x16x32_bf16 v[16:19], v[180:183], v[204:207], v[16:19]
	v_mfma_f32_16x16x32_bf16 v[4:7], v[172:175], v[240:243], v[4:7]
	v_mfma_f32_16x16x32_bf16 v[0:3], v[180:183], v[240:243], v[0:3]
	s_setprio 0
	s_barrier
	s_add_i32 s38, s38, 2
	s_add_i32 s39, s39, 0x8000
	s_cmp_gt_u32 s38, 29
	s_cbranch_scc1 .LBB0_597

.Lnb_p4:
	s_add_i32 s11, s8, 0xfff84000
	s_cmp_eq_u32 s10, 28
	s_cselect_b32 s13, s6, s11
	s_cselect_b32 s12, s7, s9
	s_or_b32 s11, s13, 0x4000
	s_mov_b32 m0, s89
	s_nop 0
	buffer_load_dwordx4 v220, s[64:67], s8 offen lds
	s_mov_b32 m0, s91
	s_nop 0
	buffer_load_dwordx4 v221, s[64:67], s8 offen lds
	s_waitcnt vmcnt(24)
	s_waitcnt lgkmcnt(0)
	s_barrier
	s_setprio 1
	s_waitcnt lgkmcnt(7)
	v_mfma_f32_16x16x32_bf16 v[164:167], v[128:131], v[184:187], 0
	v_mfma_f32_16x16x32_bf16 v[160:163], v[152:155], v[184:187], 0
	s_waitcnt lgkmcnt(5)
	v_mfma_f32_16x16x32_bf16 v[136:139], v[128:131], v[192:195], 0
	v_mfma_f32_16x16x32_bf16 v[132:135], v[152:155], v[192:195], 0
	s_waitcnt lgkmcnt(3)
	v_mfma_f32_16x16x32_bf16 v[116:119], v[128:131], v[200:203], 0
	v_mfma_f32_16x16x32_bf16 v[112:115], v[152:155], v[200:203], 0
	s_waitcnt lgkmcnt(1)
	v_mfma_f32_16x16x32_bf16 v[76:79], v[128:131], v[224:227], 0
	v_mfma_f32_16x16x32_bf16 v[72:75], v[152:155], v[224:227], 0
	v_mfma_f32_16x16x32_bf16 v[164:167], v[140:143], v[188:191], v[164:167]
	v_mfma_f32_16x16x32_bf16 v[160:163], v[156:159], v[188:191], v[160:163]
	v_mfma_f32_16x16x32_bf16 v[136:139], v[140:143], v[196:199], v[136:139]
	v_mfma_f32_16x16x32_bf16 v[132:135], v[156:159], v[196:199], v[132:135]
	v_mfma_f32_16x16x32_bf16 v[116:119], v[140:143], v[204:207], v[116:119]
	v_mfma_f32_16x16x32_bf16 v[112:115], v[156:159], v[204:207], v[112:115]
	s_waitcnt lgkmcnt(0)
	v_mfma_f32_16x16x32_bf16 v[76:79], v[140:143], v[228:231], v[76:79]
	v_mfma_f32_16x16x32_bf16 v[72:75], v[156:159], v[228:231], v[72:75]
	s_setprio 0
	s_setprio 1
	v_mfma_f32_16x16x32_bf16 v[148:151], v[168:171], v[184:187], 0
	v_mfma_f32_16x16x32_bf16 v[144:147], v[176:179], v[184:187], 0
	v_mfma_f32_16x16x32_bf16 v[124:127], v[168:171], v[192:195], 0
	v_mfma_f32_16x16x32_bf16 v[120:123], v[176:179], v[192:195], 0
	v_mfma_f32_16x16x32_bf16 v[108:111], v[168:171], v[200:203], 0
	v_mfma_f32_16x16x32_bf16 v[104:107], v[176:179], v[200:203], 0
	v_mfma_f32_16x16x32_bf16 v[68:71], v[168:171], v[224:227], 0
	v_mfma_f32_16x16x32_bf16 v[64:67], v[176:179], v[224:227], 0
	v_mfma_f32_16x16x32_bf16 v[148:151], v[172:175], v[188:191], v[148:151]
	v_mfma_f32_16x16x32_bf16 v[144:147], v[180:183], v[188:191], v[144:147]
	v_mfma_f32_16x16x32_bf16 v[124:127], v[172:175], v[196:199], v[124:127]
	v_mfma_f32_16x16x32_bf16 v[120:123], v[180:183], v[196:199], v[120:123]
	v_mfma_f32_16x16x32_bf16 v[108:111], v[172:175], v[204:207], v[108:111]
	v_mfma_f32_16x16x32_bf16 v[104:107], v[180:183], v[204:207], v[104:107]
	v_mfma_f32_16x16x32_bf16 v[68:71], v[172:175], v[228:231], v[68:71]
	v_mfma_f32_16x16x32_bf16 v[64:67], v[180:183], v[228:231], v[64:67]
	s_setprio 0
	s_barrier
	ds_read_b128 v[184:187], v223 offset:16384
	ds_read_b128 v[188:191], v223 offset:17408
	ds_read_b128 v[192:195], v223 offset:18432
	ds_read_b128 v[196:199], v223 offset:19456
	ds_read_b128 v[200:203], v223 offset:20480
	ds_read_b128 v[204:207], v223 offset:21504
	ds_read_b128 v[224:227], v223 offset:22528
	ds_read_b128 v[228:231], v223 offset:23552
	s_mov_b32 m0, s55
	s_nop 0
	buffer_load_dwordx4 v220, s[48:51], s12 offen lds
	s_add_i32 s14, s12, 0x80000
	s_mov_b32 m0, s76
	s_nop 0
	buffer_load_dwordx4 v221, s[48:51], s12 offen lds
	s_mov_b32 m0, s77
	s_nop 0
	buffer_load_dwordx4 v220, s[48:51], s14 offen lds
	s_mov_b32 m0, s78
	s_nop 0
	buffer_load_dwordx4 v221, s[48:51], s14 offen lds
	s_mov_b32 m0, s31
	s_nop 0
	buffer_load_dwordx4 v220, s[64:67], s13 offen lds
	s_mov_b32 m0, s79
	s_nop 0
	buffer_load_dwordx4 v221, s[64:67], s13 offen lds
	s_waitcnt vmcnt(24)
	s_waitcnt lgkmcnt(0)
	s_barrier
	s_setprio 1
	s_waitcnt lgkmcnt(7)
	v_mfma_f32_16x16x32_bf16 v[60:63], v[128:131], v[184:187], 0
	v_mfma_f32_16x16x32_bf16 v[56:59], v[152:155], v[184:187], 0
	s_waitcnt lgkmcnt(5)
	v_mfma_f32_16x16x32_bf16 v[44:47], v[128:131], v[192:195], 0
	v_mfma_f32_16x16x32_bf16 v[40:43], v[152:155], v[192:195], 0
	s_waitcnt lgkmcnt(3)
	v_mfma_f32_16x16x32_bf16 v[28:31], v[128:131], v[200:203], 0
	v_mfma_f32_16x16x32_bf16 v[24:27], v[152:155], v[200:203], 0
	s_waitcnt lgkmcnt(1)
	v_mfma_f32_16x16x32_bf16 v[12:15], v[128:131], v[224:227], 0
	v_mfma_f32_16x16x32_bf16 v[8:11], v[152:155], v[224:227], 0
	v_mfma_f32_16x16x32_bf16 v[60:63], v[140:143], v[188:191], v[60:63]
	v_mfma_f32_16x16x32_bf16 v[56:59], v[156:159], v[188:191], v[56:59]
	v_mfma_f32_16x16x32_bf16 v[44:47], v[140:143], v[196:199], v[44:47]
	v_mfma_f32_16x16x32_bf16 v[40:43], v[156:159], v[196:199], v[40:43]
	v_mfma_f32_16x16x32_bf16 v[28:31], v[140:143], v[204:207], v[28:31]
	v_mfma_f32_16x16x32_bf16 v[24:27], v[156:159], v[204:207], v[24:27]
	s_waitcnt lgkmcnt(0)
	v_mfma_f32_16x16x32_bf16 v[12:15], v[140:143], v[228:231], v[12:15]
	v_mfma_f32_16x16x32_bf16 v[8:11], v[156:159], v[228:231], v[8:11]
	s_setprio 0
	s_setprio 1
	v_mfma_f32_16x16x32_bf16 v[52:55], v[168:171], v[184:187], 0
	v_mfma_f32_16x16x32_bf16 v[48:51], v[176:179], v[184:187], 0
	v_mfma_f32_16x16x32_bf16 v[36:39], v[168:171], v[192:195], 0
	v_mfma_f32_16x16x32_bf16 v[32:35], v[176:179], v[192:195], 0
	v_mfma_f32_16x16x32_bf16 v[20:23], v[168:171], v[200:203], 0
	v_mfma_f32_16x16x32_bf16 v[16:19], v[176:179], v[200:203], 0
	v_mfma_f32_16x16x32_bf16 v[4:7], v[168:171], v[224:227], 0
	v_mfma_f32_16x16x32_bf16 v[0:3], v[176:179], v[224:227], 0
	v_mfma_f32_16x16x32_bf16 v[52:55], v[172:175], v[188:191], v[52:55]
	v_mfma_f32_16x16x32_bf16 v[48:51], v[180:183], v[188:191], v[48:51]
	v_mfma_f32_16x16x32_bf16 v[36:39], v[172:175], v[196:199], v[36:39]
	v_mfma_f32_16x16x32_bf16 v[32:35], v[180:183], v[196:199], v[32:35]
	v_mfma_f32_16x16x32_bf16 v[20:23], v[172:175], v[204:207], v[20:23]
	v_mfma_f32_16x16x32_bf16 v[16:19], v[180:183], v[204:207], v[16:19]
	v_mfma_f32_16x16x32_bf16 v[4:7], v[172:175], v[228:231], v[4:7]
	v_mfma_f32_16x16x32_bf16 v[0:3], v[180:183], v[228:231], v[0:3]
	s_setprio 0
	s_barrier
	v_add_u32_e32 v156, 0x18000, v222
	v_add_u32_e32 v180, 0x1c000, v222
	ds_read_b128 v[128:131], v156
	ds_read_b128 v[140:143], v156 offset:1024
	ds_read_b128 v[152:155], v156 offset:2048
	ds_read_b128 v[156:159], v156 offset:3072
	ds_read_b128 v[168:171], v180
	ds_read_b128 v[172:175], v180 offset:1024
	ds_read_b128 v[176:179], v180 offset:2048
	ds_read_b128 v[180:183], v180 offset:3072
	ds_read_b128 v[184:187], v223 offset:32768
	ds_read_b128 v[188:191], v223 offset:33792
	ds_read_b128 v[192:195], v223 offset:34816
	ds_read_b128 v[196:199], v223 offset:35840
	ds_read_b128 v[200:203], v223 offset:36864
	ds_read_b128 v[204:207], v223 offset:37888
	ds_read_b128 v[224:227], v223 offset:38912
	ds_read_b128 v[228:231], v223 offset:39936
	s_add_i32 s13, s13, 0x80000
	s_mov_b32 m0, s82
	s_nop 0
	buffer_load_dwordx4 v220, s[64:67], s13 offen lds
	s_mov_b32 m0, s83
	s_nop 0
	buffer_load_dwordx4 v221, s[64:67], s13 offen lds
	s_waitcnt vmcnt(8)
	s_waitcnt lgkmcnt(0)
	s_barrier
	s_setprio 1
	s_waitcnt lgkmcnt(7)
	v_mfma_f32_16x16x32_bf16 v[164:167], v[128:131], v[184:187], v[164:167]
	v_mfma_f32_16x16x32_bf16 v[160:163], v[152:155], v[184:187], v[160:163]
	s_waitcnt lgkmcnt(5)
	v_mfma_f32_16x16x32_bf16 v[136:139], v[128:131], v[192:195], v[136:139]
	v_mfma_f32_16x16x32_bf16 v[132:135], v[152:155], v[192:195], v[132:135]
	s_waitcnt lgkmcnt(3)
	v_mfma_f32_16x16x32_bf16 v[116:119], v[128:131], v[200:203], v[116:119]
	v_mfma_f32_16x16x32_bf16 v[112:115], v[152:155], v[200:203], v[112:115]
	s_waitcnt lgkmcnt(1)
	v_mfma_f32_16x16x32_bf16 v[76:79], v[128:131], v[224:227], v[76:79]
	v_mfma_f32_16x16x32_bf16 v[72:75], v[152:155], v[224:227], v[72:75]
	v_mfma_f32_16x16x32_bf16 v[164:167], v[140:143], v[188:191], v[164:167]
	v_mfma_f32_16x16x32_bf16 v[160:163], v[156:159], v[188:191], v[160:163]
	v_mfma_f32_16x16x32_bf16 v[136:139], v[140:143], v[196:199], v[136:139]
	v_mfma_f32_16x16x32_bf16 v[132:135], v[156:159], v[196:199], v[132:135]
	v_mfma_f32_16x16x32_bf16 v[116:119], v[140:143], v[204:207], v[116:119]
	v_mfma_f32_16x16x32_bf16 v[112:115], v[156:159], v[204:207], v[112:115]
	s_waitcnt lgkmcnt(0)
	v_mfma_f32_16x16x32_bf16 v[76:79], v[140:143], v[228:231], v[76:79]
	v_mfma_f32_16x16x32_bf16 v[72:75], v[156:159], v[228:231], v[72:75]
	s_setprio 0
	s_setprio 1
	v_mfma_f32_16x16x32_bf16 v[148:151], v[168:171], v[184:187], v[148:151]
	v_mfma_f32_16x16x32_bf16 v[144:147], v[176:179], v[184:187], v[144:147]
	v_mfma_f32_16x16x32_bf16 v[124:127], v[168:171], v[192:195], v[124:127]
	v_mfma_f32_16x16x32_bf16 v[120:123], v[176:179], v[192:195], v[120:123]
	v_mfma_f32_16x16x32_bf16 v[108:111], v[168:171], v[200:203], v[108:111]
	v_mfma_f32_16x16x32_bf16 v[104:107], v[176:179], v[200:203], v[104:107]
	v_mfma_f32_16x16x32_bf16 v[68:71], v[168:171], v[224:227], v[68:71]
	v_mfma_f32_16x16x32_bf16 v[64:67], v[176:179], v[224:227], v[64:67]
	v_mfma_f32_16x16x32_bf16 v[148:151], v[172:175], v[188:191], v[148:151]
	v_mfma_f32_16x16x32_bf16 v[144:147], v[180:183], v[188:191], v[144:147]
	v_mfma_f32_16x16x32_bf16 v[124:127], v[172:175], v[196:199], v[124:127]
	v_mfma_f32_16x16x32_bf16 v[120:123], v[180:183], v[196:199], v[120:123]
	v_mfma_f32_16x16x32_bf16 v[108:111], v[172:175], v[204:207], v[108:111]
	v_mfma_f32_16x16x32_bf16 v[104:107], v[180:183], v[204:207], v[104:107]
	v_mfma_f32_16x16x32_bf16 v[68:71], v[172:175], v[228:231], v[68:71]
	v_mfma_f32_16x16x32_bf16 v[64:67], v[180:183], v[228:231], v[64:67]
	s_setprio 0
	s_barrier
	ds_read_b128 v[184:187], v223 offset:49152
	ds_read_b128 v[188:191], v223 offset:50176
	ds_read_b128 v[192:195], v223 offset:51200
	ds_read_b128 v[196:199], v223 offset:52224
	ds_read_b128 v[200:203], v223 offset:53248
	ds_read_b128 v[204:207], v223 offset:54272
	ds_read_b128 v[224:227], v223 offset:55296
	ds_read_b128 v[228:231], v223 offset:56320
	s_or_b32 s13, s12, 0x4000
	s_mov_b32 m0, s34
	s_nop 0
	buffer_load_dwordx4 v220, s[48:51], s13 offen lds
	s_add_i32 s12, s12, 0x84000
	s_mov_b32 m0, s84
	s_nop 0
	buffer_load_dwordx4 v221, s[48:51], s13 offen lds
	s_mov_b32 m0, s87
	s_nop 0
	buffer_load_dwordx4 v220, s[48:51], s12 offen lds
	s_mov_b32 m0, s88
	s_nop 0
	buffer_load_dwordx4 v221, s[48:51], s12 offen lds
	s_mov_b32 m0, s85
	s_nop 0
	buffer_load_dwordx4 v220, s[64:67], s11 offen lds
	s_mov_b32 m0, s86
	s_nop 0
	buffer_load_dwordx4 v221, s[64:67], s11 offen lds
	s_waitcnt vmcnt(8)
	s_waitcnt lgkmcnt(0)
	s_barrier
	s_setprio 1
	s_waitcnt lgkmcnt(7)
	v_mfma_f32_16x16x32_bf16 v[60:63], v[128:131], v[184:187], v[60:63]
	v_mfma_f32_16x16x32_bf16 v[56:59], v[152:155], v[184:187], v[56:59]
	s_waitcnt lgkmcnt(5)
	v_mfma_f32_16x16x32_bf16 v[44:47], v[128:131], v[192:195], v[44:47]
	v_mfma_f32_16x16x32_bf16 v[40:43], v[152:155], v[192:195], v[40:43]
	s_waitcnt lgkmcnt(3)
	v_mfma_f32_16x16x32_bf16 v[28:31], v[128:131], v[200:203], v[28:31]
	v_mfma_f32_16x16x32_bf16 v[24:27], v[152:155], v[200:203], v[24:27]
	s_waitcnt lgkmcnt(1)
	v_mfma_f32_16x16x32_bf16 v[12:15], v[128:131], v[224:227], v[12:15]
	v_mfma_f32_16x16x32_bf16 v[8:11], v[152:155], v[224:227], v[8:11]
	v_mfma_f32_16x16x32_bf16 v[60:63], v[140:143], v[188:191], v[60:63]
	v_mfma_f32_16x16x32_bf16 v[56:59], v[156:159], v[188:191], v[56:59]
	v_mfma_f32_16x16x32_bf16 v[44:47], v[140:143], v[196:199], v[44:47]
	v_mfma_f32_16x16x32_bf16 v[40:43], v[156:159], v[196:199], v[40:43]
	v_mfma_f32_16x16x32_bf16 v[28:31], v[140:143], v[204:207], v[28:31]
	v_mfma_f32_16x16x32_bf16 v[24:27], v[156:159], v[204:207], v[24:27]
	s_waitcnt lgkmcnt(0)
	v_mfma_f32_16x16x32_bf16 v[12:15], v[140:143], v[228:231], v[12:15]
	v_mfma_f32_16x16x32_bf16 v[8:11], v[156:159], v[228:231], v[8:11]
	s_setprio 0
	s_setprio 1
	v_mfma_f32_16x16x32_bf16 v[52:55], v[168:171], v[184:187], v[52:55]
	v_mfma_f32_16x16x32_bf16 v[48:51], v[176:179], v[184:187], v[48:51]
	v_mfma_f32_16x16x32_bf16 v[36:39], v[168:171], v[192:195], v[36:39]
	v_mfma_f32_16x16x32_bf16 v[32:35], v[176:179], v[192:195], v[32:35]
	v_mfma_f32_16x16x32_bf16 v[20:23], v[168:171], v[200:203], v[20:23]
	v_mfma_f32_16x16x32_bf16 v[16:19], v[176:179], v[200:203], v[16:19]
	v_mfma_f32_16x16x32_bf16 v[4:7], v[168:171], v[224:227], v[4:7]
	v_mfma_f32_16x16x32_bf16 v[0:3], v[176:179], v[224:227], v[0:3]
	v_mfma_f32_16x16x32_bf16 v[52:55], v[172:175], v[188:191], v[52:55]
	v_mfma_f32_16x16x32_bf16 v[48:51], v[180:183], v[188:191], v[48:51]
	v_mfma_f32_16x16x32_bf16 v[36:39], v[172:175], v[196:199], v[36:39]
	v_mfma_f32_16x16x32_bf16 v[32:35], v[180:183], v[196:199], v[32:35]
	v_mfma_f32_16x16x32_bf16 v[20:23], v[172:175], v[204:207], v[20:23]
	v_mfma_f32_16x16x32_bf16 v[16:19], v[180:183], v[204:207], v[16:19]
	v_mfma_f32_16x16x32_bf16 v[4:7], v[172:175], v[228:231], v[4:7]
	v_mfma_f32_16x16x32_bf16 v[0:3], v[180:183], v[228:231], v[0:3]
	s_setprio 0
	s_barrier
	s_add_i32 s10, s10, 2
	s_add_i32 s8, s8, 0x8000
	s_add_i32 s9, s9, 0x8000
.LBB0_691:
	v_add_u32_e32 v156, 0x10000, v222
	v_add_u32_e32 v180, 0x14000, v222
	ds_read_b128 v[128:131], v156
	ds_read_b128 v[140:143], v156 offset:1024
	ds_read_b128 v[152:155], v156 offset:2048
	ds_read_b128 v[156:159], v156 offset:3072
	ds_read_b128 v[168:171], v180
	ds_read_b128 v[172:175], v180 offset:1024
	ds_read_b128 v[176:179], v180 offset:2048
	ds_read_b128 v[180:183], v180 offset:3072
	s_add_i32 s11, s8, 0xfff84000
	s_cmp_eq_u32 s10, 28
	s_cselect_b32 s13, s6, s11
	s_cselect_b32 s12, s7, s9
	s_or_b32 s11, s13, 0x4000
	ds_read_b128 v[184:187], v223
	ds_read_b128 v[188:191], v223 offset:1024
	ds_read_b128 v[192:195], v223 offset:2048
	ds_read_b128 v[196:199], v223 offset:3072
	ds_read_b128 v[200:203], v223 offset:4096
	ds_read_b128 v[204:207], v223 offset:5120
	ds_read_b128 v[224:227], v223 offset:6144
	ds_read_b128 v[228:231], v223 offset:7168
	s_mov_b32 m0, s89
	s_nop 0
	buffer_load_dwordx4 v220, s[64:67], s8 offen lds
	s_mov_b32 m0, s91
	s_nop 0
	buffer_load_dwordx4 v221, s[64:67], s8 offen lds
	s_waitcnt vmcnt(8)
	s_waitcnt lgkmcnt(0)
	s_barrier
	s_setprio 1
	s_waitcnt lgkmcnt(7)
	v_mfma_f32_16x16x32_bf16 v[164:167], v[128:131], v[184:187], v[164:167]
	v_mfma_f32_16x16x32_bf16 v[160:163], v[152:155], v[184:187], v[160:163]
	s_waitcnt lgkmcnt(5)
	v_mfma_f32_16x16x32_bf16 v[136:139], v[128:131], v[192:195], v[136:139]
	v_mfma_f32_16x16x32_bf16 v[132:135], v[152:155], v[192:195], v[132:135]
	s_waitcnt lgkmcnt(3)
	v_mfma_f32_16x16x32_bf16 v[116:119], v[128:131], v[200:203], v[116:119]
	v_mfma_f32_16x16x32_bf16 v[112:115], v[152:155], v[200:203], v[112:115]
	s_waitcnt lgkmcnt(1)
	v_mfma_f32_16x16x32_bf16 v[76:79], v[128:131], v[224:227], v[76:79]
	v_mfma_f32_16x16x32_bf16 v[72:75], v[152:155], v[224:227], v[72:75]
	v_mfma_f32_16x16x32_bf16 v[164:167], v[140:143], v[188:191], v[164:167]
	v_mfma_f32_16x16x32_bf16 v[160:163], v[156:159], v[188:191], v[160:163]
	v_mfma_f32_16x16x32_bf16 v[136:139], v[140:143], v[196:199], v[136:139]
	v_mfma_f32_16x16x32_bf16 v[132:135], v[156:159], v[196:199], v[132:135]
	v_mfma_f32_16x16x32_bf16 v[116:119], v[140:143], v[204:207], v[116:119]
	v_mfma_f32_16x16x32_bf16 v[112:115], v[156:159], v[204:207], v[112:115]
	s_waitcnt lgkmcnt(0)
	v_mfma_f32_16x16x32_bf16 v[76:79], v[140:143], v[228:231], v[76:79]
	v_mfma_f32_16x16x32_bf16 v[72:75], v[156:159], v[228:231], v[72:75]
	s_setprio 0
	s_setprio 1
	v_mfma_f32_16x16x32_bf16 v[148:151], v[168:171], v[184:187], v[148:151]
	v_mfma_f32_16x16x32_bf16 v[144:147], v[176:179], v[184:187], v[144:147]
	v_mfma_f32_16x16x32_bf16 v[124:127], v[168:171], v[192:195], v[124:127]
	v_mfma_f32_16x16x32_bf16 v[120:123], v[176:179], v[192:195], v[120:123]
	v_mfma_f32_16x16x32_bf16 v[108:111], v[168:171], v[200:203], v[108:111]
	v_mfma_f32_16x16x32_bf16 v[104:107], v[176:179], v[200:203], v[104:107]
	v_mfma_f32_16x16x32_bf16 v[68:71], v[168:171], v[224:227], v[68:71]
	v_mfma_f32_16x16x32_bf16 v[64:67], v[176:179], v[224:227], v[64:67]
	v_mfma_f32_16x16x32_bf16 v[148:151], v[172:175], v[188:191], v[148:151]
	v_mfma_f32_16x16x32_bf16 v[144:147], v[180:183], v[188:191], v[144:147]
	v_mfma_f32_16x16x32_bf16 v[124:127], v[172:175], v[196:199], v[124:127]
	v_mfma_f32_16x16x32_bf16 v[120:123], v[180:183], v[196:199], v[120:123]
	v_mfma_f32_16x16x32_bf16 v[108:111], v[172:175], v[204:207], v[108:111]
	v_mfma_f32_16x16x32_bf16 v[104:107], v[180:183], v[204:207], v[104:107]
	v_mfma_f32_16x16x32_bf16 v[68:71], v[172:175], v[228:231], v[68:71]
	v_mfma_f32_16x16x32_bf16 v[64:67], v[180:183], v[228:231], v[64:67]
	s_setprio 0
	s_barrier
	ds_read_b128 v[184:187], v223 offset:16384
	ds_read_b128 v[188:191], v223 offset:17408
	ds_read_b128 v[192:195], v223 offset:18432
	ds_read_b128 v[196:199], v223 offset:19456
	ds_read_b128 v[200:203], v223 offset:20480
	ds_read_b128 v[204:207], v223 offset:21504
	ds_read_b128 v[224:227], v223 offset:22528
	ds_read_b128 v[228:231], v223 offset:23552
	s_mov_b32 m0, s55
	s_nop 0
	buffer_load_dwordx4 v220, s[48:51], s12 offen lds
	s_add_i32 s14, s12, 0x80000
	s_mov_b32 m0, s76
	s_nop 0
	buffer_load_dwordx4 v221, s[48:51], s12 offen lds
	s_mov_b32 m0, s77
	s_nop 0
	buffer_load_dwordx4 v220, s[48:51], s14 offen lds
	s_mov_b32 m0, s78
	s_nop 0
	buffer_load_dwordx4 v221, s[48:51], s14 offen lds
	s_mov_b32 m0, s31
	s_nop 0
	buffer_load_dwordx4 v220, s[64:67], s13 offen lds
	s_mov_b32 m0, s79
	s_nop 0
	buffer_load_dwordx4 v221, s[64:67], s13 offen lds
	s_waitcnt vmcnt(8)
	s_waitcnt lgkmcnt(0)
	s_barrier
	s_setprio 1
	s_waitcnt lgkmcnt(7)
	v_mfma_f32_16x16x32_bf16 v[60:63], v[128:131], v[184:187], v[60:63]
	v_mfma_f32_16x16x32_bf16 v[56:59], v[152:155], v[184:187], v[56:59]
	s_waitcnt lgkmcnt(5)
	v_mfma_f32_16x16x32_bf16 v[44:47], v[128:131], v[192:195], v[44:47]
	v_mfma_f32_16x16x32_bf16 v[40:43], v[152:155], v[192:195], v[40:43]
	s_waitcnt lgkmcnt(3)
	v_mfma_f32_16x16x32_bf16 v[28:31], v[128:131], v[200:203], v[28:31]
	v_mfma_f32_16x16x32_bf16 v[24:27], v[152:155], v[200:203], v[24:27]
	s_waitcnt lgkmcnt(1)
	v_mfma_f32_16x16x32_bf16 v[12:15], v[128:131], v[224:227], v[12:15]
	v_mfma_f32_16x16x32_bf16 v[8:11], v[152:155], v[224:227], v[8:11]
	v_mfma_f32_16x16x32_bf16 v[60:63], v[140:143], v[188:191], v[60:63]
	v_mfma_f32_16x16x32_bf16 v[56:59], v[156:159], v[188:191], v[56:59]
	v_mfma_f32_16x16x32_bf16 v[44:47], v[140:143], v[196:199], v[44:47]
	v_mfma_f32_16x16x32_bf16 v[40:43], v[156:159], v[196:199], v[40:43]
	v_mfma_f32_16x16x32_bf16 v[28:31], v[140:143], v[204:207], v[28:31]
	v_mfma_f32_16x16x32_bf16 v[24:27], v[156:159], v[204:207], v[24:27]
	s_waitcnt lgkmcnt(0)
	v_mfma_f32_16x16x32_bf16 v[12:15], v[140:143], v[228:231], v[12:15]
	v_mfma_f32_16x16x32_bf16 v[8:11], v[156:159], v[228:231], v[8:11]
	s_setprio 0
	s_setprio 1
	v_mfma_f32_16x16x32_bf16 v[52:55], v[168:171], v[184:187], v[52:55]
	v_mfma_f32_16x16x32_bf16 v[48:51], v[176:179], v[184:187], v[48:51]
	v_mfma_f32_16x16x32_bf16 v[36:39], v[168:171], v[192:195], v[36:39]
	v_mfma_f32_16x16x32_bf16 v[32:35], v[176:179], v[192:195], v[32:35]
	v_mfma_f32_16x16x32_bf16 v[20:23], v[168:171], v[200:203], v[20:23]
	v_mfma_f32_16x16x32_bf16 v[16:19], v[176:179], v[200:203], v[16:19]
	v_mfma_f32_16x16x32_bf16 v[4:7], v[168:171], v[224:227], v[4:7]
	v_mfma_f32_16x16x32_bf16 v[0:3], v[176:179], v[224:227], v[0:3]
	v_mfma_f32_16x16x32_bf16 v[52:55], v[172:175], v[188:191], v[52:55]
	v_mfma_f32_16x16x32_bf16 v[48:51], v[180:183], v[188:191], v[48:51]
	v_mfma_f32_16x16x32_bf16 v[36:39], v[172:175], v[196:199], v[36:39]
	v_mfma_f32_16x16x32_bf16 v[32:35], v[180:183], v[196:199], v[32:35]
	v_mfma_f32_16x16x32_bf16 v[20:23], v[172:175], v[204:207], v[20:23]
	v_mfma_f32_16x16x32_bf16 v[16:19], v[180:183], v[204:207], v[16:19]
	v_mfma_f32_16x16x32_bf16 v[4:7], v[172:175], v[228:231], v[4:7]
	v_mfma_f32_16x16x32_bf16 v[0:3], v[180:183], v[228:231], v[0:3]
	s_setprio 0
	s_barrier
	v_add_u32_e32 v156, 0x18000, v222
	v_add_u32_e32 v180, 0x1c000, v222
	ds_read_b128 v[128:131], v156
	ds_read_b128 v[140:143], v156 offset:1024
	ds_read_b128 v[152:155], v156 offset:2048
	ds_read_b128 v[156:159], v156 offset:3072
	ds_read_b128 v[168:171], v180
	ds_read_b128 v[172:175], v180 offset:1024
	ds_read_b128 v[176:179], v180 offset:2048
	ds_read_b128 v[180:183], v180 offset:3072
	ds_read_b128 v[184:187], v223 offset:32768
	ds_read_b128 v[188:191], v223 offset:33792
	ds_read_b128 v[192:195], v223 offset:34816
	ds_read_b128 v[196:199], v223 offset:35840
	ds_read_b128 v[200:203], v223 offset:36864
	ds_read_b128 v[204:207], v223 offset:37888
	ds_read_b128 v[224:227], v223 offset:38912
	ds_read_b128 v[228:231], v223 offset:39936
	s_add_i32 s13, s13, 0x80000
	s_mov_b32 m0, s82
	s_nop 0
	buffer_load_dwordx4 v220, s[64:67], s13 offen lds
	s_mov_b32 m0, s83
	s_nop 0
	buffer_load_dwordx4 v221, s[64:67], s13 offen lds
	s_waitcnt vmcnt(8)
	s_waitcnt lgkmcnt(0)
	s_barrier
	s_setprio 1
	s_waitcnt lgkmcnt(7)
	v_mfma_f32_16x16x32_bf16 v[164:167], v[128:131], v[184:187], v[164:167]
	v_mfma_f32_16x16x32_bf16 v[160:163], v[152:155], v[184:187], v[160:163]
	s_waitcnt lgkmcnt(5)
	v_mfma_f32_16x16x32_bf16 v[136:139], v[128:131], v[192:195], v[136:139]
	v_mfma_f32_16x16x32_bf16 v[132:135], v[152:155], v[192:195], v[132:135]
	s_waitcnt lgkmcnt(3)
	v_mfma_f32_16x16x32_bf16 v[116:119], v[128:131], v[200:203], v[116:119]
	v_mfma_f32_16x16x32_bf16 v[112:115], v[152:155], v[200:203], v[112:115]
	s_waitcnt lgkmcnt(1)
	v_mfma_f32_16x16x32_bf16 v[76:79], v[128:131], v[224:227], v[76:79]
	v_mfma_f32_16x16x32_bf16 v[72:75], v[152:155], v[224:227], v[72:75]
	v_mfma_f32_16x16x32_bf16 v[164:167], v[140:143], v[188:191], v[164:167]
	v_mfma_f32_16x16x32_bf16 v[160:163], v[156:159], v[188:191], v[160:163]
	v_mfma_f32_16x16x32_bf16 v[136:139], v[140:143], v[196:199], v[136:139]
	v_mfma_f32_16x16x32_bf16 v[132:135], v[156:159], v[196:199], v[132:135]
	v_mfma_f32_16x16x32_bf16 v[116:119], v[140:143], v[204:207], v[116:119]
	v_mfma_f32_16x16x32_bf16 v[112:115], v[156:159], v[204:207], v[112:115]
	s_waitcnt lgkmcnt(0)
	v_mfma_f32_16x16x32_bf16 v[76:79], v[140:143], v[228:231], v[76:79]
	v_mfma_f32_16x16x32_bf16 v[72:75], v[156:159], v[228:231], v[72:75]
	s_setprio 0
	s_setprio 1
	v_mfma_f32_16x16x32_bf16 v[148:151], v[168:171], v[184:187], v[148:151]
	v_mfma_f32_16x16x32_bf16 v[144:147], v[176:179], v[184:187], v[144:147]
	v_mfma_f32_16x16x32_bf16 v[124:127], v[168:171], v[192:195], v[124:127]
	v_mfma_f32_16x16x32_bf16 v[120:123], v[176:179], v[192:195], v[120:123]
	v_mfma_f32_16x16x32_bf16 v[108:111], v[168:171], v[200:203], v[108:111]
	v_mfma_f32_16x16x32_bf16 v[104:107], v[176:179], v[200:203], v[104:107]
	v_mfma_f32_16x16x32_bf16 v[68:71], v[168:171], v[224:227], v[68:71]
	v_mfma_f32_16x16x32_bf16 v[64:67], v[176:179], v[224:227], v[64:67]
	v_mfma_f32_16x16x32_bf16 v[148:151], v[172:175], v[188:191], v[148:151]
	v_mfma_f32_16x16x32_bf16 v[144:147], v[180:183], v[188:191], v[144:147]
	v_mfma_f32_16x16x32_bf16 v[124:127], v[172:175], v[196:199], v[124:127]
	v_mfma_f32_16x16x32_bf16 v[120:123], v[180:183], v[196:199], v[120:123]
	v_mfma_f32_16x16x32_bf16 v[108:111], v[172:175], v[204:207], v[108:111]
	v_mfma_f32_16x16x32_bf16 v[104:107], v[180:183], v[204:207], v[104:107]
	v_mfma_f32_16x16x32_bf16 v[68:71], v[172:175], v[228:231], v[68:71]
	v_mfma_f32_16x16x32_bf16 v[64:67], v[180:183], v[228:231], v[64:67]
	s_setprio 0
	s_barrier
	ds_read_b128 v[184:187], v223 offset:49152
	ds_read_b128 v[188:191], v223 offset:50176
	ds_read_b128 v[192:195], v223 offset:51200
	ds_read_b128 v[196:199], v223 offset:52224
	ds_read_b128 v[200:203], v223 offset:53248
	ds_read_b128 v[204:207], v223 offset:54272
	ds_read_b128 v[224:227], v223 offset:55296
	ds_read_b128 v[228:231], v223 offset:56320
	s_or_b32 s13, s12, 0x4000
	s_mov_b32 m0, s34
	s_nop 0
	buffer_load_dwordx4 v220, s[48:51], s13 offen lds
	s_add_i32 s12, s12, 0x84000
	s_mov_b32 m0, s84
	s_nop 0
	buffer_load_dwordx4 v221, s[48:51], s13 offen lds
	s_mov_b32 m0, s87
	s_nop 0
	buffer_load_dwordx4 v220, s[48:51], s12 offen lds
	s_mov_b32 m0, s88
	s_nop 0
	buffer_load_dwordx4 v221, s[48:51], s12 offen lds
	s_mov_b32 m0, s85
	s_nop 0
	buffer_load_dwordx4 v220, s[64:67], s11 offen lds
	s_mov_b32 m0, s86
	s_nop 0
	buffer_load_dwordx4 v221, s[64:67], s11 offen lds
	s_waitcnt vmcnt(8)
	s_waitcnt lgkmcnt(0)
	s_barrier
	s_setprio 1
	s_waitcnt lgkmcnt(7)
	v_mfma_f32_16x16x32_bf16 v[60:63], v[128:131], v[184:187], v[60:63]
	v_mfma_f32_16x16x32_bf16 v[56:59], v[152:155], v[184:187], v[56:59]
	s_waitcnt lgkmcnt(5)
	v_mfma_f32_16x16x32_bf16 v[44:47], v[128:131], v[192:195], v[44:47]
	v_mfma_f32_16x16x32_bf16 v[40:43], v[152:155], v[192:195], v[40:43]
	s_waitcnt lgkmcnt(3)
	v_mfma_f32_16x16x32_bf16 v[28:31], v[128:131], v[200:203], v[28:31]
	v_mfma_f32_16x16x32_bf16 v[24:27], v[152:155], v[200:203], v[24:27]
	s_waitcnt lgkmcnt(1)
	v_mfma_f32_16x16x32_bf16 v[12:15], v[128:131], v[224:227], v[12:15]
	v_mfma_f32_16x16x32_bf16 v[8:11], v[152:155], v[224:227], v[8:11]
	v_mfma_f32_16x16x32_bf16 v[60:63], v[140:143], v[188:191], v[60:63]
	v_mfma_f32_16x16x32_bf16 v[56:59], v[156:159], v[188:191], v[56:59]
	v_mfma_f32_16x16x32_bf16 v[44:47], v[140:143], v[196:199], v[44:47]
	v_mfma_f32_16x16x32_bf16 v[40:43], v[156:159], v[196:199], v[40:43]
	v_mfma_f32_16x16x32_bf16 v[28:31], v[140:143], v[204:207], v[28:31]
	v_mfma_f32_16x16x32_bf16 v[24:27], v[156:159], v[204:207], v[24:27]
	s_waitcnt lgkmcnt(0)
	v_mfma_f32_16x16x32_bf16 v[12:15], v[140:143], v[228:231], v[12:15]
	v_mfma_f32_16x16x32_bf16 v[8:11], v[156:159], v[228:231], v[8:11]
	s_setprio 0
	s_setprio 1
	v_mfma_f32_16x16x32_bf16 v[52:55], v[168:171], v[184:187], v[52:55]
	v_mfma_f32_16x16x32_bf16 v[48:51], v[176:179], v[184:187], v[48:51]
	v_mfma_f32_16x16x32_bf16 v[36:39], v[168:171], v[192:195], v[36:39]
	v_mfma_f32_16x16x32_bf16 v[32:35], v[176:179], v[192:195], v[32:35]
	v_mfma_f32_16x16x32_bf16 v[20:23], v[168:171], v[200:203], v[20:23]
	v_mfma_f32_16x16x32_bf16 v[16:19], v[176:179], v[200:203], v[16:19]
	v_mfma_f32_16x16x32_bf16 v[4:7], v[168:171], v[224:227], v[4:7]
	v_mfma_f32_16x16x32_bf16 v[0:3], v[176:179], v[224:227], v[0:3]
	v_mfma_f32_16x16x32_bf16 v[52:55], v[172:175], v[188:191], v[52:55]
	v_mfma_f32_16x16x32_bf16 v[48:51], v[180:183], v[188:191], v[48:51]
	v_mfma_f32_16x16x32_bf16 v[36:39], v[172:175], v[196:199], v[36:39]
	v_mfma_f32_16x16x32_bf16 v[32:35], v[180:183], v[196:199], v[32:35]
	v_mfma_f32_16x16x32_bf16 v[20:23], v[172:175], v[204:207], v[20:23]
	v_mfma_f32_16x16x32_bf16 v[16:19], v[180:183], v[204:207], v[16:19]
	v_mfma_f32_16x16x32_bf16 v[4:7], v[172:175], v[228:231], v[4:7]
	v_mfma_f32_16x16x32_bf16 v[0:3], v[180:183], v[228:231], v[0:3]
	s_setprio 0
	s_barrier
	s_add_i32 s10, s10, 2
	s_add_i32 s8, s8, 0x8000
	s_add_i32 s9, s9, 0x8000
	s_cmp_gt_u32 s10, 29
	s_cbranch_scc0 .LBB0_691
	s_and_b64 vcc, exec, s[2:3]
	s_cbranch_vccz .LBB0_694
	s_barrier

.Lnb_p5:
	s_add_i32 s53, s37, 0xfff84000
	s_cmp_eq_u32 s52, 28
	s_cselect_b32 s56, s4, s53
	s_cselect_b32 s55, s5, s51
	s_or_b32 s53, s56, 0x4000
	s_mov_b32 m0, s41
	s_nop 0
	buffer_load_dwordx4 v166, s[24:27], s37 offen lds
	s_mov_b32 m0, s42
	s_nop 0
	buffer_load_dwordx4 v167, s[24:27], s37 offen lds
	s_waitcnt vmcnt(24)
	s_waitcnt lgkmcnt(0)
	s_barrier
	s_setprio 1
	s_waitcnt lgkmcnt(7)
	v_mfma_f32_16x16x32_bf16 v[148:151], v[152:155], v[190:193], 0
	v_mfma_f32_16x16x32_bf16 v[140:143], v[160:163], v[190:193], 0
	s_waitcnt lgkmcnt(5)
	v_mfma_f32_16x16x32_bf16 v[132:135], v[152:155], v[198:201], 0
	v_mfma_f32_16x16x32_bf16 v[124:127], v[160:163], v[198:201], 0
	s_waitcnt lgkmcnt(3)
	v_mfma_f32_16x16x32_bf16 v[116:119], v[152:155], v[220:223], 0
	v_mfma_f32_16x16x32_bf16 v[108:111], v[160:163], v[220:223], 0
	s_waitcnt lgkmcnt(1)
	v_mfma_f32_16x16x32_bf16 v[76:79], v[152:155], v[228:231], 0
	v_mfma_f32_16x16x32_bf16 v[68:71], v[160:163], v[228:231], 0
	v_mfma_f32_16x16x32_bf16 v[148:151], v[156:159], v[194:197], v[148:151]
	v_mfma_f32_16x16x32_bf16 v[140:143], v[170:173], v[194:197], v[140:143]
	v_mfma_f32_16x16x32_bf16 v[132:135], v[156:159], v[202:205], v[132:135]
	v_mfma_f32_16x16x32_bf16 v[124:127], v[170:173], v[202:205], v[124:127]
	v_mfma_f32_16x16x32_bf16 v[116:119], v[156:159], v[224:227], v[116:119]
	v_mfma_f32_16x16x32_bf16 v[108:111], v[170:173], v[224:227], v[108:111]
	s_waitcnt lgkmcnt(0)
	v_mfma_f32_16x16x32_bf16 v[76:79], v[156:159], v[240:243], v[76:79]
	v_mfma_f32_16x16x32_bf16 v[68:71], v[170:173], v[240:243], v[68:71]
	s_setprio 0
	s_setprio 1
	v_mfma_f32_16x16x32_bf16 v[144:147], v[174:177], v[190:193], 0
	v_mfma_f32_16x16x32_bf16 v[136:139], v[182:185], v[190:193], 0
	v_mfma_f32_16x16x32_bf16 v[128:131], v[174:177], v[198:201], 0
	v_mfma_f32_16x16x32_bf16 v[120:123], v[182:185], v[198:201], 0
	v_mfma_f32_16x16x32_bf16 v[112:115], v[174:177], v[220:223], 0
	v_mfma_f32_16x16x32_bf16 v[104:107], v[182:185], v[220:223], 0
	v_mfma_f32_16x16x32_bf16 v[72:75], v[174:177], v[228:231], 0
	v_mfma_f32_16x16x32_bf16 v[64:67], v[182:185], v[228:231], 0
	v_mfma_f32_16x16x32_bf16 v[144:147], v[178:181], v[194:197], v[144:147]
	v_mfma_f32_16x16x32_bf16 v[136:139], v[186:189], v[194:197], v[136:139]
	v_mfma_f32_16x16x32_bf16 v[128:131], v[178:181], v[202:205], v[128:131]
	v_mfma_f32_16x16x32_bf16 v[120:123], v[186:189], v[202:205], v[120:123]
	v_mfma_f32_16x16x32_bf16 v[112:115], v[178:181], v[224:227], v[112:115]
	v_mfma_f32_16x16x32_bf16 v[104:107], v[186:189], v[224:227], v[104:107]
	v_mfma_f32_16x16x32_bf16 v[72:75], v[178:181], v[240:243], v[72:75]
	v_mfma_f32_16x16x32_bf16 v[64:67], v[186:189], v[240:243], v[64:67]
	s_setprio 0
	s_barrier
	ds_read_b128 v[190:193], v169 offset:16384
	ds_read_b128 v[194:197], v169 offset:17408
	ds_read_b128 v[198:201], v169 offset:18432
	ds_read_b128 v[202:205], v169 offset:19456
	ds_read_b128 v[220:223], v169 offset:20480
	ds_read_b128 v[224:227], v169 offset:21504
	ds_read_b128 v[228:231], v169 offset:22528
	ds_read_b128 v[240:243], v169 offset:23552
	s_mov_b32 m0, s7
	s_nop 0
	buffer_load_dwordx4 v166, s[28:31], s55 offen lds
	s_add_i32 s57, s55, 0x80000
	s_mov_b32 m0, s8
	s_nop 0
	buffer_load_dwordx4 v167, s[28:31], s55 offen lds
	s_mov_b32 m0, s9
	s_nop 0
	buffer_load_dwordx4 v166, s[28:31], s57 offen lds
	s_mov_b32 m0, s10
	s_nop 0
	buffer_load_dwordx4 v167, s[28:31], s57 offen lds
	s_mov_b32 m0, s6
	s_nop 0
	buffer_load_dwordx4 v166, s[24:27], s56 offen lds
	s_mov_b32 m0, s11
	s_nop 0
	buffer_load_dwordx4 v167, s[24:27], s56 offen lds
	s_waitcnt vmcnt(24)
	s_waitcnt lgkmcnt(0)
	s_barrier
	s_setprio 1
	s_waitcnt lgkmcnt(7)
	v_mfma_f32_16x16x32_bf16 v[60:63], v[152:155], v[190:193], 0
	v_mfma_f32_16x16x32_bf16 v[52:55], v[160:163], v[190:193], 0
	s_waitcnt lgkmcnt(5)
	v_mfma_f32_16x16x32_bf16 v[44:47], v[152:155], v[198:201], 0
	v_mfma_f32_16x16x32_bf16 v[36:39], v[160:163], v[198:201], 0
	s_waitcnt lgkmcnt(3)
	v_mfma_f32_16x16x32_bf16 v[28:31], v[152:155], v[220:223], 0
	v_mfma_f32_16x16x32_bf16 v[20:23], v[160:163], v[220:223], 0
	s_waitcnt lgkmcnt(1)
	v_mfma_f32_16x16x32_bf16 v[12:15], v[152:155], v[228:231], 0
	v_mfma_f32_16x16x32_bf16 v[4:7], v[160:163], v[228:231], 0
	v_mfma_f32_16x16x32_bf16 v[60:63], v[156:159], v[194:197], v[60:63]
	v_mfma_f32_16x16x32_bf16 v[52:55], v[170:173], v[194:197], v[52:55]
	v_mfma_f32_16x16x32_bf16 v[44:47], v[156:159], v[202:205], v[44:47]
	v_mfma_f32_16x16x32_bf16 v[36:39], v[170:173], v[202:205], v[36:39]
	v_mfma_f32_16x16x32_bf16 v[28:31], v[156:159], v[224:227], v[28:31]
	v_mfma_f32_16x16x32_bf16 v[20:23], v[170:173], v[224:227], v[20:23]
	s_waitcnt lgkmcnt(0)
	v_mfma_f32_16x16x32_bf16 v[12:15], v[156:159], v[240:243], v[12:15]
	v_mfma_f32_16x16x32_bf16 v[4:7], v[170:173], v[240:243], v[4:7]
	s_setprio 0
	s_setprio 1
	v_mfma_f32_16x16x32_bf16 v[56:59], v[174:177], v[190:193], 0
	v_mfma_f32_16x16x32_bf16 v[48:51], v[182:185], v[190:193], 0
	v_mfma_f32_16x16x32_bf16 v[40:43], v[174:177], v[198:201], 0
	v_mfma_f32_16x16x32_bf16 v[32:35], v[182:185], v[198:201], 0
	v_mfma_f32_16x16x32_bf16 v[24:27], v[174:177], v[220:223], 0
	v_mfma_f32_16x16x32_bf16 v[16:19], v[182:185], v[220:223], 0
	v_mfma_f32_16x16x32_bf16 v[8:11], v[174:177], v[228:231], 0
	v_mfma_f32_16x16x32_bf16 v[0:3], v[182:185], v[228:231], 0
	v_mfma_f32_16x16x32_bf16 v[56:59], v[178:181], v[194:197], v[56:59]
	v_mfma_f32_16x16x32_bf16 v[48:51], v[186:189], v[194:197], v[48:51]
	v_mfma_f32_16x16x32_bf16 v[40:43], v[178:181], v[202:205], v[40:43]
	v_mfma_f32_16x16x32_bf16 v[32:35], v[186:189], v[202:205], v[32:35]
	v_mfma_f32_16x16x32_bf16 v[24:27], v[178:181], v[224:227], v[24:27]
	v_mfma_f32_16x16x32_bf16 v[16:19], v[186:189], v[224:227], v[16:19]
	v_mfma_f32_16x16x32_bf16 v[8:11], v[178:181], v[240:243], v[8:11]
	v_mfma_f32_16x16x32_bf16 v[0:3], v[186:189], v[240:243], v[0:3]
	s_setprio 0
	s_barrier
	v_add_u32_e32 v164, 0x18000, v168
	ds_read_b128 v[152:155], v164
	ds_read_b128 v[156:159], v164 offset:1024
	ds_read_b128 v[160:163], v164 offset:2048
	ds_read_b128 v[170:173], v164 offset:3072
	v_add_u32_e32 v164, 0x1c000, v168
	ds_read_b128 v[174:177], v164
	ds_read_b128 v[178:181], v164 offset:1024
	ds_read_b128 v[182:185], v164 offset:2048
	ds_read_b128 v[186:189], v164 offset:3072
	ds_read_b128 v[190:193], v169 offset:32768
	ds_read_b128 v[194:197], v169 offset:33792
	ds_read_b128 v[198:201], v169 offset:34816
	ds_read_b128 v[202:205], v169 offset:35840
	ds_read_b128 v[220:223], v169 offset:36864
	ds_read_b128 v[224:227], v169 offset:37888
	ds_read_b128 v[228:231], v169 offset:38912
	ds_read_b128 v[240:243], v169 offset:39936
	s_add_i32 s56, s56, 0x80000
	s_mov_b32 m0, s12
	s_nop 0
	buffer_load_dwordx4 v166, s[24:27], s56 offen lds
	s_mov_b32 m0, s13
	s_nop 0
	buffer_load_dwordx4 v167, s[24:27], s56 offen lds
	s_waitcnt vmcnt(8)
	s_waitcnt lgkmcnt(0)
	s_barrier
	s_setprio 1
	s_waitcnt lgkmcnt(7)
	v_mfma_f32_16x16x32_bf16 v[148:151], v[152:155], v[190:193], v[148:151]
	v_mfma_f32_16x16x32_bf16 v[140:143], v[160:163], v[190:193], v[140:143]
	s_waitcnt lgkmcnt(5)
	v_mfma_f32_16x16x32_bf16 v[132:135], v[152:155], v[198:201], v[132:135]
	v_mfma_f32_16x16x32_bf16 v[124:127], v[160:163], v[198:201], v[124:127]
	s_waitcnt lgkmcnt(3)
	v_mfma_f32_16x16x32_bf16 v[116:119], v[152:155], v[220:223], v[116:119]
	v_mfma_f32_16x16x32_bf16 v[108:111], v[160:163], v[220:223], v[108:111]
	s_waitcnt lgkmcnt(1)
	v_mfma_f32_16x16x32_bf16 v[76:79], v[152:155], v[228:231], v[76:79]
	v_mfma_f32_16x16x32_bf16 v[68:71], v[160:163], v[228:231], v[68:71]
	v_mfma_f32_16x16x32_bf16 v[148:151], v[156:159], v[194:197], v[148:151]
	v_mfma_f32_16x16x32_bf16 v[140:143], v[170:173], v[194:197], v[140:143]
	v_mfma_f32_16x16x32_bf16 v[132:135], v[156:159], v[202:205], v[132:135]
	v_mfma_f32_16x16x32_bf16 v[124:127], v[170:173], v[202:205], v[124:127]
	v_mfma_f32_16x16x32_bf16 v[116:119], v[156:159], v[224:227], v[116:119]
	v_mfma_f32_16x16x32_bf16 v[108:111], v[170:173], v[224:227], v[108:111]
	s_waitcnt lgkmcnt(0)
	v_mfma_f32_16x16x32_bf16 v[76:79], v[156:159], v[240:243], v[76:79]
	v_mfma_f32_16x16x32_bf16 v[68:71], v[170:173], v[240:243], v[68:71]
	s_setprio 0
	s_setprio 1
	v_mfma_f32_16x16x32_bf16 v[144:147], v[174:177], v[190:193], v[144:147]
	v_mfma_f32_16x16x32_bf16 v[136:139], v[182:185], v[190:193], v[136:139]
	v_mfma_f32_16x16x32_bf16 v[128:131], v[174:177], v[198:201], v[128:131]
	v_mfma_f32_16x16x32_bf16 v[120:123], v[182:185], v[198:201], v[120:123]
	v_mfma_f32_16x16x32_bf16 v[112:115], v[174:177], v[220:223], v[112:115]
	v_mfma_f32_16x16x32_bf16 v[104:107], v[182:185], v[220:223], v[104:107]
	v_mfma_f32_16x16x32_bf16 v[72:75], v[174:177], v[228:231], v[72:75]
	v_mfma_f32_16x16x32_bf16 v[64:67], v[182:185], v[228:231], v[64:67]
	v_mfma_f32_16x16x32_bf16 v[144:147], v[178:181], v[194:197], v[144:147]
	v_mfma_f32_16x16x32_bf16 v[136:139], v[186:189], v[194:197], v[136:139]
	v_mfma_f32_16x16x32_bf16 v[128:131], v[178:181], v[202:205], v[128:131]
	v_mfma_f32_16x16x32_bf16 v[120:123], v[186:189], v[202:205], v[120:123]
	v_mfma_f32_16x16x32_bf16 v[112:115], v[178:181], v[224:227], v[112:115]
	v_mfma_f32_16x16x32_bf16 v[104:107], v[186:189], v[224:227], v[104:107]
	v_mfma_f32_16x16x32_bf16 v[72:75], v[178:181], v[240:243], v[72:75]
	v_mfma_f32_16x16x32_bf16 v[64:67], v[186:189], v[240:243], v[64:67]
	s_setprio 0
	s_barrier
	ds_read_b128 v[190:193], v169 offset:49152
	ds_read_b128 v[194:197], v169 offset:50176
	ds_read_b128 v[198:201], v169 offset:51200
	ds_read_b128 v[202:205], v169 offset:52224
	ds_read_b128 v[220:223], v169 offset:53248
	ds_read_b128 v[224:227], v169 offset:54272
	ds_read_b128 v[228:231], v169 offset:55296
	ds_read_b128 v[240:243], v169 offset:56320
	s_or_b32 s56, s55, 0x4000
	s_mov_b32 m0, s16
	s_nop 0
	buffer_load_dwordx4 v166, s[28:31], s56 offen lds
	s_add_i32 s55, s55, 0x84000
	s_mov_b32 m0, s17
	s_nop 0
	buffer_load_dwordx4 v167, s[28:31], s56 offen lds
	s_mov_b32 m0, s34
	s_nop 0
	buffer_load_dwordx4 v166, s[28:31], s55 offen lds
	s_mov_b32 m0, s40
	s_nop 0
	buffer_load_dwordx4 v167, s[28:31], s55 offen lds
	s_mov_b32 m0, s18
	s_nop 0
	buffer_load_dwordx4 v166, s[24:27], s53 offen lds
	s_mov_b32 m0, s19
	s_nop 0
	buffer_load_dwordx4 v167, s[24:27], s53 offen lds
	s_waitcnt vmcnt(8)
	s_waitcnt lgkmcnt(0)
	s_barrier
	s_setprio 1
	s_waitcnt lgkmcnt(7)
	v_mfma_f32_16x16x32_bf16 v[60:63], v[152:155], v[190:193], v[60:63]
	v_mfma_f32_16x16x32_bf16 v[52:55], v[160:163], v[190:193], v[52:55]
	s_waitcnt lgkmcnt(5)
	v_mfma_f32_16x16x32_bf16 v[44:47], v[152:155], v[198:201], v[44:47]
	v_mfma_f32_16x16x32_bf16 v[36:39], v[160:163], v[198:201], v[36:39]
	s_waitcnt lgkmcnt(3)
	v_mfma_f32_16x16x32_bf16 v[28:31], v[152:155], v[220:223], v[28:31]
	v_mfma_f32_16x16x32_bf16 v[20:23], v[160:163], v[220:223], v[20:23]
	s_waitcnt lgkmcnt(1)
	v_mfma_f32_16x16x32_bf16 v[12:15], v[152:155], v[228:231], v[12:15]
	v_mfma_f32_16x16x32_bf16 v[4:7], v[160:163], v[228:231], v[4:7]
	v_mfma_f32_16x16x32_bf16 v[60:63], v[156:159], v[194:197], v[60:63]
	v_mfma_f32_16x16x32_bf16 v[52:55], v[170:173], v[194:197], v[52:55]
	v_mfma_f32_16x16x32_bf16 v[44:47], v[156:159], v[202:205], v[44:47]
	v_mfma_f32_16x16x32_bf16 v[36:39], v[170:173], v[202:205], v[36:39]
	v_mfma_f32_16x16x32_bf16 v[28:31], v[156:159], v[224:227], v[28:31]
	v_mfma_f32_16x16x32_bf16 v[20:23], v[170:173], v[224:227], v[20:23]
	s_waitcnt lgkmcnt(0)
	v_mfma_f32_16x16x32_bf16 v[12:15], v[156:159], v[240:243], v[12:15]
	v_mfma_f32_16x16x32_bf16 v[4:7], v[170:173], v[240:243], v[4:7]
	s_setprio 0
	s_setprio 1
	v_mfma_f32_16x16x32_bf16 v[56:59], v[174:177], v[190:193], v[56:59]
	v_mfma_f32_16x16x32_bf16 v[48:51], v[182:185], v[190:193], v[48:51]
	v_mfma_f32_16x16x32_bf16 v[40:43], v[174:177], v[198:201], v[40:43]
	v_mfma_f32_16x16x32_bf16 v[32:35], v[182:185], v[198:201], v[32:35]
	v_mfma_f32_16x16x32_bf16 v[24:27], v[174:177], v[220:223], v[24:27]
	v_mfma_f32_16x16x32_bf16 v[16:19], v[182:185], v[220:223], v[16:19]
	v_mfma_f32_16x16x32_bf16 v[8:11], v[174:177], v[228:231], v[8:11]
	v_mfma_f32_16x16x32_bf16 v[0:3], v[182:185], v[228:231], v[0:3]
	v_mfma_f32_16x16x32_bf16 v[56:59], v[178:181], v[194:197], v[56:59]
	v_mfma_f32_16x16x32_bf16 v[48:51], v[186:189], v[194:197], v[48:51]
	v_mfma_f32_16x16x32_bf16 v[40:43], v[178:181], v[202:205], v[40:43]
	v_mfma_f32_16x16x32_bf16 v[32:35], v[186:189], v[202:205], v[32:35]
	v_mfma_f32_16x16x32_bf16 v[24:27], v[178:181], v[224:227], v[24:27]
	v_mfma_f32_16x16x32_bf16 v[16:19], v[186:189], v[224:227], v[16:19]
	v_mfma_f32_16x16x32_bf16 v[8:11], v[178:181], v[240:243], v[8:11]
	v_mfma_f32_16x16x32_bf16 v[0:3], v[186:189], v[240:243], v[0:3]
	s_setprio 0
	s_barrier
	s_add_i32 s52, s52, 2
	s_add_i32 s37, s37, 0x8000
	s_add_i32 s51, s51, 0x8000
.LBB0_795:
	v_add_u32_e32 v164, 0x10000, v168
	ds_read_b128 v[152:155], v164
	ds_read_b128 v[156:159], v164 offset:1024
	ds_read_b128 v[160:163], v164 offset:2048
	ds_read_b128 v[170:173], v164 offset:3072
	v_add_u32_e32 v164, 0x14000, v168
	ds_read_b128 v[174:177], v164
	ds_read_b128 v[178:181], v164 offset:1024
	ds_read_b128 v[182:185], v164 offset:2048
	ds_read_b128 v[186:189], v164 offset:3072
	s_add_i32 s53, s37, 0xfff84000
	s_cmp_eq_u32 s52, 28
	s_cselect_b32 s56, s4, s53
	s_cselect_b32 s55, s5, s51
	s_or_b32 s53, s56, 0x4000
	ds_read_b128 v[190:193], v169
	ds_read_b128 v[194:197], v169 offset:1024
	ds_read_b128 v[198:201], v169 offset:2048
	ds_read_b128 v[202:205], v169 offset:3072
	ds_read_b128 v[220:223], v169 offset:4096
	ds_read_b128 v[224:227], v169 offset:5120
	ds_read_b128 v[228:231], v169 offset:6144
	ds_read_b128 v[240:243], v169 offset:7168
	s_mov_b32 m0, s41
	s_nop 0
	buffer_load_dwordx4 v166, s[24:27], s37 offen lds
	s_mov_b32 m0, s42
	s_nop 0
	buffer_load_dwordx4 v167, s[24:27], s37 offen lds
	s_waitcnt vmcnt(8)
	s_waitcnt lgkmcnt(0)
	s_barrier
	s_setprio 1
	s_waitcnt lgkmcnt(7)
	v_mfma_f32_16x16x32_bf16 v[148:151], v[152:155], v[190:193], v[148:151]
	v_mfma_f32_16x16x32_bf16 v[140:143], v[160:163], v[190:193], v[140:143]
	s_waitcnt lgkmcnt(5)
	v_mfma_f32_16x16x32_bf16 v[132:135], v[152:155], v[198:201], v[132:135]
	v_mfma_f32_16x16x32_bf16 v[124:127], v[160:163], v[198:201], v[124:127]
	s_waitcnt lgkmcnt(3)
	v_mfma_f32_16x16x32_bf16 v[116:119], v[152:155], v[220:223], v[116:119]
	v_mfma_f32_16x16x32_bf16 v[108:111], v[160:163], v[220:223], v[108:111]
	s_waitcnt lgkmcnt(1)
	v_mfma_f32_16x16x32_bf16 v[76:79], v[152:155], v[228:231], v[76:79]
	v_mfma_f32_16x16x32_bf16 v[68:71], v[160:163], v[228:231], v[68:71]
	v_mfma_f32_16x16x32_bf16 v[148:151], v[156:159], v[194:197], v[148:151]
	v_mfma_f32_16x16x32_bf16 v[140:143], v[170:173], v[194:197], v[140:143]
	v_mfma_f32_16x16x32_bf16 v[132:135], v[156:159], v[202:205], v[132:135]
	v_mfma_f32_16x16x32_bf16 v[124:127], v[170:173], v[202:205], v[124:127]
	v_mfma_f32_16x16x32_bf16 v[116:119], v[156:159], v[224:227], v[116:119]
	v_mfma_f32_16x16x32_bf16 v[108:111], v[170:173], v[224:227], v[108:111]
	s_waitcnt lgkmcnt(0)
	v_mfma_f32_16x16x32_bf16 v[76:79], v[156:159], v[240:243], v[76:79]
	v_mfma_f32_16x16x32_bf16 v[68:71], v[170:173], v[240:243], v[68:71]
	s_setprio 0
	s_setprio 1
	v_mfma_f32_16x16x32_bf16 v[144:147], v[174:177], v[190:193], v[144:147]
	v_mfma_f32_16x16x32_bf16 v[136:139], v[182:185], v[190:193], v[136:139]
	v_mfma_f32_16x16x32_bf16 v[128:131], v[174:177], v[198:201], v[128:131]
	v_mfma_f32_16x16x32_bf16 v[120:123], v[182:185], v[198:201], v[120:123]
	v_mfma_f32_16x16x32_bf16 v[112:115], v[174:177], v[220:223], v[112:115]
	v_mfma_f32_16x16x32_bf16 v[104:107], v[182:185], v[220:223], v[104:107]
	v_mfma_f32_16x16x32_bf16 v[72:75], v[174:177], v[228:231], v[72:75]
	v_mfma_f32_16x16x32_bf16 v[64:67], v[182:185], v[228:231], v[64:67]
	v_mfma_f32_16x16x32_bf16 v[144:147], v[178:181], v[194:197], v[144:147]
	v_mfma_f32_16x16x32_bf16 v[136:139], v[186:189], v[194:197], v[136:139]
	v_mfma_f32_16x16x32_bf16 v[128:131], v[178:181], v[202:205], v[128:131]
	v_mfma_f32_16x16x32_bf16 v[120:123], v[186:189], v[202:205], v[120:123]
	v_mfma_f32_16x16x32_bf16 v[112:115], v[178:181], v[224:227], v[112:115]
	v_mfma_f32_16x16x32_bf16 v[104:107], v[186:189], v[224:227], v[104:107]
	v_mfma_f32_16x16x32_bf16 v[72:75], v[178:181], v[240:243], v[72:75]
	v_mfma_f32_16x16x32_bf16 v[64:67], v[186:189], v[240:243], v[64:67]
	s_setprio 0
	s_barrier
	ds_read_b128 v[190:193], v169 offset:16384
	ds_read_b128 v[194:197], v169 offset:17408
	ds_read_b128 v[198:201], v169 offset:18432
	ds_read_b128 v[202:205], v169 offset:19456
	ds_read_b128 v[220:223], v169 offset:20480
	ds_read_b128 v[224:227], v169 offset:21504
	ds_read_b128 v[228:231], v169 offset:22528
	ds_read_b128 v[240:243], v169 offset:23552
	s_mov_b32 m0, s7
	s_nop 0
	buffer_load_dwordx4 v166, s[28:31], s55 offen lds
	s_add_i32 s57, s55, 0x80000
	s_mov_b32 m0, s8
	s_nop 0
	buffer_load_dwordx4 v167, s[28:31], s55 offen lds
	s_mov_b32 m0, s9
	s_nop 0
	buffer_load_dwordx4 v166, s[28:31], s57 offen lds
	s_mov_b32 m0, s10
	s_nop 0
	buffer_load_dwordx4 v167, s[28:31], s57 offen lds
	s_mov_b32 m0, s6
	s_nop 0
	buffer_load_dwordx4 v166, s[24:27], s56 offen lds
	s_mov_b32 m0, s11
	s_nop 0
	buffer_load_dwordx4 v167, s[24:27], s56 offen lds
	s_waitcnt vmcnt(8)
	s_waitcnt lgkmcnt(0)
	s_barrier
	s_setprio 1
	s_waitcnt lgkmcnt(7)
	v_mfma_f32_16x16x32_bf16 v[60:63], v[152:155], v[190:193], v[60:63]
	v_mfma_f32_16x16x32_bf16 v[52:55], v[160:163], v[190:193], v[52:55]
	s_waitcnt lgkmcnt(5)
	v_mfma_f32_16x16x32_bf16 v[44:47], v[152:155], v[198:201], v[44:47]
	v_mfma_f32_16x16x32_bf16 v[36:39], v[160:163], v[198:201], v[36:39]
	s_waitcnt lgkmcnt(3)
	v_mfma_f32_16x16x32_bf16 v[28:31], v[152:155], v[220:223], v[28:31]
	v_mfma_f32_16x16x32_bf16 v[20:23], v[160:163], v[220:223], v[20:23]
	s_waitcnt lgkmcnt(1)
	v_mfma_f32_16x16x32_bf16 v[12:15], v[152:155], v[228:231], v[12:15]
	v_mfma_f32_16x16x32_bf16 v[4:7], v[160:163], v[228:231], v[4:7]
	v_mfma_f32_16x16x32_bf16 v[60:63], v[156:159], v[194:197], v[60:63]
	v_mfma_f32_16x16x32_bf16 v[52:55], v[170:173], v[194:197], v[52:55]
	v_mfma_f32_16x16x32_bf16 v[44:47], v[156:159], v[202:205], v[44:47]
	v_mfma_f32_16x16x32_bf16 v[36:39], v[170:173], v[202:205], v[36:39]
	v_mfma_f32_16x16x32_bf16 v[28:31], v[156:159], v[224:227], v[28:31]
	v_mfma_f32_16x16x32_bf16 v[20:23], v[170:173], v[224:227], v[20:23]
	s_waitcnt lgkmcnt(0)
	v_mfma_f32_16x16x32_bf16 v[12:15], v[156:159], v[240:243], v[12:15]
	v_mfma_f32_16x16x32_bf16 v[4:7], v[170:173], v[240:243], v[4:7]
	s_setprio 0
	s_setprio 1
	v_mfma_f32_16x16x32_bf16 v[56:59], v[174:177], v[190:193], v[56:59]
	v_mfma_f32_16x16x32_bf16 v[48:51], v[182:185], v[190:193], v[48:51]
	v_mfma_f32_16x16x32_bf16 v[40:43], v[174:177], v[198:201], v[40:43]
	v_mfma_f32_16x16x32_bf16 v[32:35], v[182:185], v[198:201], v[32:35]
	v_mfma_f32_16x16x32_bf16 v[24:27], v[174:177], v[220:223], v[24:27]
	v_mfma_f32_16x16x32_bf16 v[16:19], v[182:185], v[220:223], v[16:19]
	v_mfma_f32_16x16x32_bf16 v[8:11], v[174:177], v[228:231], v[8:11]
	v_mfma_f32_16x16x32_bf16 v[0:3], v[182:185], v[228:231], v[0:3]
	v_mfma_f32_16x16x32_bf16 v[56:59], v[178:181], v[194:197], v[56:59]
	v_mfma_f32_16x16x32_bf16 v[48:51], v[186:189], v[194:197], v[48:51]
	v_mfma_f32_16x16x32_bf16 v[40:43], v[178:181], v[202:205], v[40:43]
	v_mfma_f32_16x16x32_bf16 v[32:35], v[186:189], v[202:205], v[32:35]
	v_mfma_f32_16x16x32_bf16 v[24:27], v[178:181], v[224:227], v[24:27]
	v_mfma_f32_16x16x32_bf16 v[16:19], v[186:189], v[224:227], v[16:19]
	v_mfma_f32_16x16x32_bf16 v[8:11], v[178:181], v[240:243], v[8:11]
	v_mfma_f32_16x16x32_bf16 v[0:3], v[186:189], v[240:243], v[0:3]
	s_setprio 0
	s_barrier
	v_add_u32_e32 v164, 0x18000, v168
	ds_read_b128 v[152:155], v164
	ds_read_b128 v[156:159], v164 offset:1024
	ds_read_b128 v[160:163], v164 offset:2048
	ds_read_b128 v[170:173], v164 offset:3072
	v_add_u32_e32 v164, 0x1c000, v168
	ds_read_b128 v[174:177], v164
	ds_read_b128 v[178:181], v164 offset:1024
	ds_read_b128 v[182:185], v164 offset:2048
	ds_read_b128 v[186:189], v164 offset:3072
	ds_read_b128 v[190:193], v169 offset:32768
	ds_read_b128 v[194:197], v169 offset:33792
	ds_read_b128 v[198:201], v169 offset:34816
	ds_read_b128 v[202:205], v169 offset:35840
	ds_read_b128 v[220:223], v169 offset:36864
	ds_read_b128 v[224:227], v169 offset:37888
	ds_read_b128 v[228:231], v169 offset:38912
	ds_read_b128 v[240:243], v169 offset:39936
	s_add_i32 s56, s56, 0x80000
	s_mov_b32 m0, s12
	s_nop 0
	buffer_load_dwordx4 v166, s[24:27], s56 offen lds
	s_mov_b32 m0, s13
	s_nop 0
	buffer_load_dwordx4 v167, s[24:27], s56 offen lds
	s_waitcnt vmcnt(8)
	s_waitcnt lgkmcnt(0)
	s_barrier
	s_setprio 1
	s_waitcnt lgkmcnt(7)
	v_mfma_f32_16x16x32_bf16 v[148:151], v[152:155], v[190:193], v[148:151]
	v_mfma_f32_16x16x32_bf16 v[140:143], v[160:163], v[190:193], v[140:143]
	s_waitcnt lgkmcnt(5)
	v_mfma_f32_16x16x32_bf16 v[132:135], v[152:155], v[198:201], v[132:135]
	v_mfma_f32_16x16x32_bf16 v[124:127], v[160:163], v[198:201], v[124:127]
	s_waitcnt lgkmcnt(3)
	v_mfma_f32_16x16x32_bf16 v[116:119], v[152:155], v[220:223], v[116:119]
	v_mfma_f32_16x16x32_bf16 v[108:111], v[160:163], v[220:223], v[108:111]
	s_waitcnt lgkmcnt(1)
	v_mfma_f32_16x16x32_bf16 v[76:79], v[152:155], v[228:231], v[76:79]
	v_mfma_f32_16x16x32_bf16 v[68:71], v[160:163], v[228:231], v[68:71]
	v_mfma_f32_16x16x32_bf16 v[148:151], v[156:159], v[194:197], v[148:151]
	v_mfma_f32_16x16x32_bf16 v[140:143], v[170:173], v[194:197], v[140:143]
	v_mfma_f32_16x16x32_bf16 v[132:135], v[156:159], v[202:205], v[132:135]
	v_mfma_f32_16x16x32_bf16 v[124:127], v[170:173], v[202:205], v[124:127]
	v_mfma_f32_16x16x32_bf16 v[116:119], v[156:159], v[224:227], v[116:119]
	v_mfma_f32_16x16x32_bf16 v[108:111], v[170:173], v[224:227], v[108:111]
	s_waitcnt lgkmcnt(0)
	v_mfma_f32_16x16x32_bf16 v[76:79], v[156:159], v[240:243], v[76:79]
	v_mfma_f32_16x16x32_bf16 v[68:71], v[170:173], v[240:243], v[68:71]
	s_setprio 0
	s_setprio 1
	v_mfma_f32_16x16x32_bf16 v[144:147], v[174:177], v[190:193], v[144:147]
	v_mfma_f32_16x16x32_bf16 v[136:139], v[182:185], v[190:193], v[136:139]
	v_mfma_f32_16x16x32_bf16 v[128:131], v[174:177], v[198:201], v[128:131]
	v_mfma_f32_16x16x32_bf16 v[120:123], v[182:185], v[198:201], v[120:123]
	v_mfma_f32_16x16x32_bf16 v[112:115], v[174:177], v[220:223], v[112:115]
	v_mfma_f32_16x16x32_bf16 v[104:107], v[182:185], v[220:223], v[104:107]
	v_mfma_f32_16x16x32_bf16 v[72:75], v[174:177], v[228:231], v[72:75]
	v_mfma_f32_16x16x32_bf16 v[64:67], v[182:185], v[228:231], v[64:67]
	v_mfma_f32_16x16x32_bf16 v[144:147], v[178:181], v[194:197], v[144:147]
	v_mfma_f32_16x16x32_bf16 v[136:139], v[186:189], v[194:197], v[136:139]
	v_mfma_f32_16x16x32_bf16 v[128:131], v[178:181], v[202:205], v[128:131]
	v_mfma_f32_16x16x32_bf16 v[120:123], v[186:189], v[202:205], v[120:123]
	v_mfma_f32_16x16x32_bf16 v[112:115], v[178:181], v[224:227], v[112:115]
	v_mfma_f32_16x16x32_bf16 v[104:107], v[186:189], v[224:227], v[104:107]
	v_mfma_f32_16x16x32_bf16 v[72:75], v[178:181], v[240:243], v[72:75]
	v_mfma_f32_16x16x32_bf16 v[64:67], v[186:189], v[240:243], v[64:67]
	s_setprio 0
	s_barrier
	ds_read_b128 v[190:193], v169 offset:49152
	ds_read_b128 v[194:197], v169 offset:50176
	ds_read_b128 v[198:201], v169 offset:51200
	ds_read_b128 v[202:205], v169 offset:52224
	ds_read_b128 v[220:223], v169 offset:53248
	ds_read_b128 v[224:227], v169 offset:54272
	ds_read_b128 v[228:231], v169 offset:55296
	ds_read_b128 v[240:243], v169 offset:56320
	s_or_b32 s56, s55, 0x4000
	s_mov_b32 m0, s16
	s_nop 0
	buffer_load_dwordx4 v166, s[28:31], s56 offen lds
	s_add_i32 s55, s55, 0x84000
	s_mov_b32 m0, s17
	s_nop 0
	buffer_load_dwordx4 v167, s[28:31], s56 offen lds
	s_mov_b32 m0, s34
	s_nop 0
	buffer_load_dwordx4 v166, s[28:31], s55 offen lds
	s_mov_b32 m0, s40
	s_nop 0
	buffer_load_dwordx4 v167, s[28:31], s55 offen lds
	s_mov_b32 m0, s18
	s_nop 0
	buffer_load_dwordx4 v166, s[24:27], s53 offen lds
	s_mov_b32 m0, s19
	s_nop 0
	buffer_load_dwordx4 v167, s[24:27], s53 offen lds
	s_waitcnt vmcnt(8)
	s_waitcnt lgkmcnt(0)
	s_barrier
	s_setprio 1
	s_waitcnt lgkmcnt(7)
	v_mfma_f32_16x16x32_bf16 v[60:63], v[152:155], v[190:193], v[60:63]
	v_mfma_f32_16x16x32_bf16 v[52:55], v[160:163], v[190:193], v[52:55]
	s_waitcnt lgkmcnt(5)
	v_mfma_f32_16x16x32_bf16 v[44:47], v[152:155], v[198:201], v[44:47]
	v_mfma_f32_16x16x32_bf16 v[36:39], v[160:163], v[198:201], v[36:39]
	s_waitcnt lgkmcnt(3)
	v_mfma_f32_16x16x32_bf16 v[28:31], v[152:155], v[220:223], v[28:31]
	v_mfma_f32_16x16x32_bf16 v[20:23], v[160:163], v[220:223], v[20:23]
	s_waitcnt lgkmcnt(1)
	v_mfma_f32_16x16x32_bf16 v[12:15], v[152:155], v[228:231], v[12:15]
	v_mfma_f32_16x16x32_bf16 v[4:7], v[160:163], v[228:231], v[4:7]
	v_mfma_f32_16x16x32_bf16 v[60:63], v[156:159], v[194:197], v[60:63]
	v_mfma_f32_16x16x32_bf16 v[52:55], v[170:173], v[194:197], v[52:55]
	v_mfma_f32_16x16x32_bf16 v[44:47], v[156:159], v[202:205], v[44:47]
	v_mfma_f32_16x16x32_bf16 v[36:39], v[170:173], v[202:205], v[36:39]
	v_mfma_f32_16x16x32_bf16 v[28:31], v[156:159], v[224:227], v[28:31]
	v_mfma_f32_16x16x32_bf16 v[20:23], v[170:173], v[224:227], v[20:23]
	s_waitcnt lgkmcnt(0)
	v_mfma_f32_16x16x32_bf16 v[12:15], v[156:159], v[240:243], v[12:15]
	v_mfma_f32_16x16x32_bf16 v[4:7], v[170:173], v[240:243], v[4:7]
	s_setprio 0
	s_setprio 1
	v_mfma_f32_16x16x32_bf16 v[56:59], v[174:177], v[190:193], v[56:59]
	v_mfma_f32_16x16x32_bf16 v[48:51], v[182:185], v[190:193], v[48:51]
	v_mfma_f32_16x16x32_bf16 v[40:43], v[174:177], v[198:201], v[40:43]
	v_mfma_f32_16x16x32_bf16 v[32:35], v[182:185], v[198:201], v[32:35]
	v_mfma_f32_16x16x32_bf16 v[24:27], v[174:177], v[220:223], v[24:27]
	v_mfma_f32_16x16x32_bf16 v[16:19], v[182:185], v[220:223], v[16:19]
	v_mfma_f32_16x16x32_bf16 v[8:11], v[174:177], v[228:231], v[8:11]
	v_mfma_f32_16x16x32_bf16 v[0:3], v[182:185], v[228:231], v[0:3]
	v_mfma_f32_16x16x32_bf16 v[56:59], v[178:181], v[194:197], v[56:59]
	v_mfma_f32_16x16x32_bf16 v[48:51], v[186:189], v[194:197], v[48:51]
	v_mfma_f32_16x16x32_bf16 v[40:43], v[178:181], v[202:205], v[40:43]
	v_mfma_f32_16x16x32_bf16 v[32:35], v[186:189], v[202:205], v[32:35]
	v_mfma_f32_16x16x32_bf16 v[24:27], v[178:181], v[224:227], v[24:27]
	v_mfma_f32_16x16x32_bf16 v[16:19], v[186:189], v[224:227], v[16:19]
	v_mfma_f32_16x16x32_bf16 v[8:11], v[178:181], v[240:243], v[8:11]
	v_mfma_f32_16x16x32_bf16 v[0:3], v[186:189], v[240:243], v[0:3]
	s_setprio 0
	s_barrier
	s_add_i32 s52, s52, 2
	s_add_i32 s37, s37, 0x8000
	s_add_i32 s51, s51, 0x8000
	s_cmp_gt_u32 s52, 29
	s_cbranch_scc0 .LBB0_795
	s_and_b64 vcc, exec, s[2:3]
	s_cbranch_vccz .LBB0_798
	s_barrier

.Lnb_p6:
	s_add_i32 s11, s8, 0xffea4000
	s_cmpk_eq_i32 s10, 0x54
	s_cselect_b32 s13, s6, s11
	s_cselect_b32 s12, s7, s9
	s_or_b32 s11, s13, 0x4000
	s_mov_b32 m0, s87
	s_nop 0
	buffer_load_dwordx4 v220, s[20:23], s8 offen lds
	s_mov_b32 m0, s89
	s_nop 0
	buffer_load_dwordx4 v221, s[20:23], s8 offen lds
	s_waitcnt vmcnt(24)
	s_waitcnt lgkmcnt(0)
	s_barrier
	s_setprio 1
	s_waitcnt lgkmcnt(7)
	v_mfma_f32_16x16x32_bf16 v[164:167], v[128:131], v[184:187], 0
	v_mfma_f32_16x16x32_bf16 v[160:163], v[152:155], v[184:187], 0
	s_waitcnt lgkmcnt(5)
	v_mfma_f32_16x16x32_bf16 v[136:139], v[128:131], v[192:195], 0
	v_mfma_f32_16x16x32_bf16 v[132:135], v[152:155], v[192:195], 0
	s_waitcnt lgkmcnt(3)
	v_mfma_f32_16x16x32_bf16 v[116:119], v[128:131], v[200:203], 0
	v_mfma_f32_16x16x32_bf16 v[112:115], v[152:155], v[200:203], 0
	s_waitcnt lgkmcnt(1)
	v_mfma_f32_16x16x32_bf16 v[76:79], v[128:131], v[224:227], 0
	v_mfma_f32_16x16x32_bf16 v[72:75], v[152:155], v[224:227], 0
	v_mfma_f32_16x16x32_bf16 v[164:167], v[140:143], v[188:191], v[164:167]
	v_mfma_f32_16x16x32_bf16 v[160:163], v[156:159], v[188:191], v[160:163]
	v_mfma_f32_16x16x32_bf16 v[136:139], v[140:143], v[196:199], v[136:139]
	v_mfma_f32_16x16x32_bf16 v[132:135], v[156:159], v[196:199], v[132:135]
	v_mfma_f32_16x16x32_bf16 v[116:119], v[140:143], v[204:207], v[116:119]
	v_mfma_f32_16x16x32_bf16 v[112:115], v[156:159], v[204:207], v[112:115]
	s_waitcnt lgkmcnt(0)
	v_mfma_f32_16x16x32_bf16 v[76:79], v[140:143], v[228:231], v[76:79]
	v_mfma_f32_16x16x32_bf16 v[72:75], v[156:159], v[228:231], v[72:75]
	s_setprio 0
	s_setprio 1
	v_mfma_f32_16x16x32_bf16 v[148:151], v[168:171], v[184:187], 0
	v_mfma_f32_16x16x32_bf16 v[144:147], v[176:179], v[184:187], 0
	v_mfma_f32_16x16x32_bf16 v[124:127], v[168:171], v[192:195], 0
	v_mfma_f32_16x16x32_bf16 v[120:123], v[176:179], v[192:195], 0
	v_mfma_f32_16x16x32_bf16 v[108:111], v[168:171], v[200:203], 0
	v_mfma_f32_16x16x32_bf16 v[104:107], v[176:179], v[200:203], 0
	v_mfma_f32_16x16x32_bf16 v[68:71], v[168:171], v[224:227], 0
	v_mfma_f32_16x16x32_bf16 v[64:67], v[176:179], v[224:227], 0
	v_mfma_f32_16x16x32_bf16 v[148:151], v[172:175], v[188:191], v[148:151]
	v_mfma_f32_16x16x32_bf16 v[144:147], v[180:183], v[188:191], v[144:147]
	v_mfma_f32_16x16x32_bf16 v[124:127], v[172:175], v[196:199], v[124:127]
	v_mfma_f32_16x16x32_bf16 v[120:123], v[180:183], v[196:199], v[120:123]
	v_mfma_f32_16x16x32_bf16 v[108:111], v[172:175], v[204:207], v[108:111]
	v_mfma_f32_16x16x32_bf16 v[104:107], v[180:183], v[204:207], v[104:107]
	v_mfma_f32_16x16x32_bf16 v[68:71], v[172:175], v[228:231], v[68:71]
	v_mfma_f32_16x16x32_bf16 v[64:67], v[180:183], v[228:231], v[64:67]
	s_setprio 0
	s_barrier
	ds_read_b128 v[184:187], v223 offset:16384
	ds_read_b128 v[188:191], v223 offset:17408
	ds_read_b128 v[192:195], v223 offset:18432
	ds_read_b128 v[196:199], v223 offset:19456
	ds_read_b128 v[200:203], v223 offset:20480
	ds_read_b128 v[204:207], v223 offset:21504
	ds_read_b128 v[224:227], v223 offset:22528
	ds_read_b128 v[228:231], v223 offset:23552
	s_mov_b32 m0, s51
	s_nop 0
	buffer_load_dwordx4 v220, s[52:55], s12 offen lds
	s_add_i32 s14, s12, 0x160000
	s_mov_b32 m0, s74
	s_nop 0
	buffer_load_dwordx4 v221, s[52:55], s12 offen lds
	s_mov_b32 m0, s75
	s_nop 0
	buffer_load_dwordx4 v220, s[52:55], s14 offen lds
	s_mov_b32 m0, s76
	s_nop 0
	buffer_load_dwordx4 v221, s[52:55], s14 offen lds
	s_mov_b32 m0, s31
	s_nop 0
	buffer_load_dwordx4 v220, s[20:23], s13 offen lds
	s_mov_b32 m0, s77
	s_nop 0
	buffer_load_dwordx4 v221, s[20:23], s13 offen lds
	s_waitcnt vmcnt(24)
	s_waitcnt lgkmcnt(0)
	s_barrier
	s_setprio 1
	s_waitcnt lgkmcnt(7)
	v_mfma_f32_16x16x32_bf16 v[60:63], v[128:131], v[184:187], 0
	v_mfma_f32_16x16x32_bf16 v[56:59], v[152:155], v[184:187], 0
	s_waitcnt lgkmcnt(5)
	v_mfma_f32_16x16x32_bf16 v[44:47], v[128:131], v[192:195], 0
	v_mfma_f32_16x16x32_bf16 v[40:43], v[152:155], v[192:195], 0
	s_waitcnt lgkmcnt(3)
	v_mfma_f32_16x16x32_bf16 v[28:31], v[128:131], v[200:203], 0
	v_mfma_f32_16x16x32_bf16 v[24:27], v[152:155], v[200:203], 0
	s_waitcnt lgkmcnt(1)
	v_mfma_f32_16x16x32_bf16 v[12:15], v[128:131], v[224:227], 0
	v_mfma_f32_16x16x32_bf16 v[8:11], v[152:155], v[224:227], 0
	v_mfma_f32_16x16x32_bf16 v[60:63], v[140:143], v[188:191], v[60:63]
	v_mfma_f32_16x16x32_bf16 v[56:59], v[156:159], v[188:191], v[56:59]
	v_mfma_f32_16x16x32_bf16 v[44:47], v[140:143], v[196:199], v[44:47]
	v_mfma_f32_16x16x32_bf16 v[40:43], v[156:159], v[196:199], v[40:43]
	v_mfma_f32_16x16x32_bf16 v[28:31], v[140:143], v[204:207], v[28:31]
	v_mfma_f32_16x16x32_bf16 v[24:27], v[156:159], v[204:207], v[24:27]
	s_waitcnt lgkmcnt(0)
	v_mfma_f32_16x16x32_bf16 v[12:15], v[140:143], v[228:231], v[12:15]
	v_mfma_f32_16x16x32_bf16 v[8:11], v[156:159], v[228:231], v[8:11]
	s_setprio 0
	s_setprio 1
	v_mfma_f32_16x16x32_bf16 v[52:55], v[168:171], v[184:187], 0
	v_mfma_f32_16x16x32_bf16 v[48:51], v[176:179], v[184:187], 0
	v_mfma_f32_16x16x32_bf16 v[36:39], v[168:171], v[192:195], 0
	v_mfma_f32_16x16x32_bf16 v[32:35], v[176:179], v[192:195], 0
	v_mfma_f32_16x16x32_bf16 v[20:23], v[168:171], v[200:203], 0
	v_mfma_f32_16x16x32_bf16 v[16:19], v[176:179], v[200:203], 0
	v_mfma_f32_16x16x32_bf16 v[4:7], v[168:171], v[224:227], 0
	v_mfma_f32_16x16x32_bf16 v[0:3], v[176:179], v[224:227], 0
	v_mfma_f32_16x16x32_bf16 v[52:55], v[172:175], v[188:191], v[52:55]
	v_mfma_f32_16x16x32_bf16 v[48:51], v[180:183], v[188:191], v[48:51]
	v_mfma_f32_16x16x32_bf16 v[36:39], v[172:175], v[196:199], v[36:39]
	v_mfma_f32_16x16x32_bf16 v[32:35], v[180:183], v[196:199], v[32:35]
	v_mfma_f32_16x16x32_bf16 v[20:23], v[172:175], v[204:207], v[20:23]
	v_mfma_f32_16x16x32_bf16 v[16:19], v[180:183], v[204:207], v[16:19]
	v_mfma_f32_16x16x32_bf16 v[4:7], v[172:175], v[228:231], v[4:7]
	v_mfma_f32_16x16x32_bf16 v[0:3], v[180:183], v[228:231], v[0:3]
	s_setprio 0
	s_barrier
	v_add_u32_e32 v156, 0x18000, v222
	v_add_u32_e32 v180, 0x1c000, v222
	ds_read_b128 v[128:131], v156
	ds_read_b128 v[140:143], v156 offset:1024
	ds_read_b128 v[152:155], v156 offset:2048
	ds_read_b128 v[156:159], v156 offset:3072
	ds_read_b128 v[168:171], v180
	ds_read_b128 v[172:175], v180 offset:1024
	ds_read_b128 v[176:179], v180 offset:2048
	ds_read_b128 v[180:183], v180 offset:3072
	ds_read_b128 v[184:187], v223 offset:32768
	ds_read_b128 v[188:191], v223 offset:33792
	ds_read_b128 v[192:195], v223 offset:34816
	ds_read_b128 v[196:199], v223 offset:35840
	ds_read_b128 v[200:203], v223 offset:36864
	ds_read_b128 v[204:207], v223 offset:37888
	ds_read_b128 v[224:227], v223 offset:38912
	ds_read_b128 v[228:231], v223 offset:39936
	s_add_i32 s13, s13, 0x160000
	s_mov_b32 m0, s78
	s_nop 0
	buffer_load_dwordx4 v220, s[20:23], s13 offen lds
	s_mov_b32 m0, s79
	s_nop 0
	buffer_load_dwordx4 v221, s[20:23], s13 offen lds
	s_waitcnt vmcnt(8)
	s_waitcnt lgkmcnt(0)
	s_barrier
	s_setprio 1
	s_waitcnt lgkmcnt(7)
	v_mfma_f32_16x16x32_bf16 v[164:167], v[128:131], v[184:187], v[164:167]
	v_mfma_f32_16x16x32_bf16 v[160:163], v[152:155], v[184:187], v[160:163]
	s_waitcnt lgkmcnt(5)
	v_mfma_f32_16x16x32_bf16 v[136:139], v[128:131], v[192:195], v[136:139]
	v_mfma_f32_16x16x32_bf16 v[132:135], v[152:155], v[192:195], v[132:135]
	s_waitcnt lgkmcnt(3)
	v_mfma_f32_16x16x32_bf16 v[116:119], v[128:131], v[200:203], v[116:119]
	v_mfma_f32_16x16x32_bf16 v[112:115], v[152:155], v[200:203], v[112:115]
	s_waitcnt lgkmcnt(1)
	v_mfma_f32_16x16x32_bf16 v[76:79], v[128:131], v[224:227], v[76:79]
	v_mfma_f32_16x16x32_bf16 v[72:75], v[152:155], v[224:227], v[72:75]
	v_mfma_f32_16x16x32_bf16 v[164:167], v[140:143], v[188:191], v[164:167]
	v_mfma_f32_16x16x32_bf16 v[160:163], v[156:159], v[188:191], v[160:163]
	v_mfma_f32_16x16x32_bf16 v[136:139], v[140:143], v[196:199], v[136:139]
	v_mfma_f32_16x16x32_bf16 v[132:135], v[156:159], v[196:199], v[132:135]
	v_mfma_f32_16x16x32_bf16 v[116:119], v[140:143], v[204:207], v[116:119]
	v_mfma_f32_16x16x32_bf16 v[112:115], v[156:159], v[204:207], v[112:115]
	s_waitcnt lgkmcnt(0)
	v_mfma_f32_16x16x32_bf16 v[76:79], v[140:143], v[228:231], v[76:79]
	v_mfma_f32_16x16x32_bf16 v[72:75], v[156:159], v[228:231], v[72:75]
	s_setprio 0
	s_setprio 1
	v_mfma_f32_16x16x32_bf16 v[148:151], v[168:171], v[184:187], v[148:151]
	v_mfma_f32_16x16x32_bf16 v[144:147], v[176:179], v[184:187], v[144:147]
	v_mfma_f32_16x16x32_bf16 v[124:127], v[168:171], v[192:195], v[124:127]
	v_mfma_f32_16x16x32_bf16 v[120:123], v[176:179], v[192:195], v[120:123]
	v_mfma_f32_16x16x32_bf16 v[108:111], v[168:171], v[200:203], v[108:111]
	v_mfma_f32_16x16x32_bf16 v[104:107], v[176:179], v[200:203], v[104:107]
	v_mfma_f32_16x16x32_bf16 v[68:71], v[168:171], v[224:227], v[68:71]
	v_mfma_f32_16x16x32_bf16 v[64:67], v[176:179], v[224:227], v[64:67]
	v_mfma_f32_16x16x32_bf16 v[148:151], v[172:175], v[188:191], v[148:151]
	v_mfma_f32_16x16x32_bf16 v[144:147], v[180:183], v[188:191], v[144:147]
	v_mfma_f32_16x16x32_bf16 v[124:127], v[172:175], v[196:199], v[124:127]
	v_mfma_f32_16x16x32_bf16 v[120:123], v[180:183], v[196:199], v[120:123]
	v_mfma_f32_16x16x32_bf16 v[108:111], v[172:175], v[204:207], v[108:111]
	v_mfma_f32_16x16x32_bf16 v[104:107], v[180:183], v[204:207], v[104:107]
	v_mfma_f32_16x16x32_bf16 v[68:71], v[172:175], v[228:231], v[68:71]
	v_mfma_f32_16x16x32_bf16 v[64:67], v[180:183], v[228:231], v[64:67]
	s_setprio 0
	s_barrier
	ds_read_b128 v[184:187], v223 offset:49152
	ds_read_b128 v[188:191], v223 offset:50176
	ds_read_b128 v[192:195], v223 offset:51200
	ds_read_b128 v[196:199], v223 offset:52224
	ds_read_b128 v[200:203], v223 offset:53248
	ds_read_b128 v[204:207], v223 offset:54272
	ds_read_b128 v[224:227], v223 offset:55296
	ds_read_b128 v[228:231], v223 offset:56320
	s_or_b32 s13, s12, 0x4000
	s_mov_b32 m0, s34
	s_nop 0
	buffer_load_dwordx4 v220, s[52:55], s13 offen lds
	s_add_i32 s12, s12, 0x164000
	s_mov_b32 m0, s82
	s_nop 0
	buffer_load_dwordx4 v221, s[52:55], s13 offen lds
	s_mov_b32 m0, s85
	s_nop 0
	buffer_load_dwordx4 v220, s[52:55], s12 offen lds
	s_mov_b32 m0, s86
	s_nop 0
	buffer_load_dwordx4 v221, s[52:55], s12 offen lds
	s_mov_b32 m0, s83
	s_nop 0
	buffer_load_dwordx4 v220, s[20:23], s11 offen lds
	s_mov_b32 m0, s84
	s_nop 0
	buffer_load_dwordx4 v221, s[20:23], s11 offen lds
	s_waitcnt vmcnt(8)
	s_waitcnt lgkmcnt(0)
	s_barrier
	s_setprio 1
	s_waitcnt lgkmcnt(7)
	v_mfma_f32_16x16x32_bf16 v[60:63], v[128:131], v[184:187], v[60:63]
	v_mfma_f32_16x16x32_bf16 v[56:59], v[152:155], v[184:187], v[56:59]
	s_waitcnt lgkmcnt(5)
	v_mfma_f32_16x16x32_bf16 v[44:47], v[128:131], v[192:195], v[44:47]
	v_mfma_f32_16x16x32_bf16 v[40:43], v[152:155], v[192:195], v[40:43]
	s_waitcnt lgkmcnt(3)
	v_mfma_f32_16x16x32_bf16 v[28:31], v[128:131], v[200:203], v[28:31]
	v_mfma_f32_16x16x32_bf16 v[24:27], v[152:155], v[200:203], v[24:27]
	s_waitcnt lgkmcnt(1)
	v_mfma_f32_16x16x32_bf16 v[12:15], v[128:131], v[224:227], v[12:15]
	v_mfma_f32_16x16x32_bf16 v[8:11], v[152:155], v[224:227], v[8:11]
	v_mfma_f32_16x16x32_bf16 v[60:63], v[140:143], v[188:191], v[60:63]
	v_mfma_f32_16x16x32_bf16 v[56:59], v[156:159], v[188:191], v[56:59]
	v_mfma_f32_16x16x32_bf16 v[44:47], v[140:143], v[196:199], v[44:47]
	v_mfma_f32_16x16x32_bf16 v[40:43], v[156:159], v[196:199], v[40:43]
	v_mfma_f32_16x16x32_bf16 v[28:31], v[140:143], v[204:207], v[28:31]
	v_mfma_f32_16x16x32_bf16 v[24:27], v[156:159], v[204:207], v[24:27]
	s_waitcnt lgkmcnt(0)
	v_mfma_f32_16x16x32_bf16 v[12:15], v[140:143], v[228:231], v[12:15]
	v_mfma_f32_16x16x32_bf16 v[8:11], v[156:159], v[228:231], v[8:11]
	s_setprio 0
	s_setprio 1
	v_mfma_f32_16x16x32_bf16 v[52:55], v[168:171], v[184:187], v[52:55]
	v_mfma_f32_16x16x32_bf16 v[48:51], v[176:179], v[184:187], v[48:51]
	v_mfma_f32_16x16x32_bf16 v[36:39], v[168:171], v[192:195], v[36:39]
	v_mfma_f32_16x16x32_bf16 v[32:35], v[176:179], v[192:195], v[32:35]
	v_mfma_f32_16x16x32_bf16 v[20:23], v[168:171], v[200:203], v[20:23]
	v_mfma_f32_16x16x32_bf16 v[16:19], v[176:179], v[200:203], v[16:19]
	v_mfma_f32_16x16x32_bf16 v[4:7], v[168:171], v[224:227], v[4:7]
	v_mfma_f32_16x16x32_bf16 v[0:3], v[176:179], v[224:227], v[0:3]
	v_mfma_f32_16x16x32_bf16 v[52:55], v[172:175], v[188:191], v[52:55]
	v_mfma_f32_16x16x32_bf16 v[48:51], v[180:183], v[188:191], v[48:51]
	v_mfma_f32_16x16x32_bf16 v[36:39], v[172:175], v[196:199], v[36:39]
	v_mfma_f32_16x16x32_bf16 v[32:35], v[180:183], v[196:199], v[32:35]
	v_mfma_f32_16x16x32_bf16 v[20:23], v[172:175], v[204:207], v[20:23]
	v_mfma_f32_16x16x32_bf16 v[16:19], v[180:183], v[204:207], v[16:19]
	v_mfma_f32_16x16x32_bf16 v[4:7], v[172:175], v[228:231], v[4:7]
	v_mfma_f32_16x16x32_bf16 v[0:3], v[180:183], v[228:231], v[0:3]
	s_setprio 0
	s_barrier
	s_add_i32 s10, s10, 2
	s_add_i32 s8, s8, 0x8000
	s_add_i32 s9, s9, 0x8000
.LBB0_885:
	v_add_u32_e32 v156, 0x10000, v222
	v_add_u32_e32 v180, 0x14000, v222
	ds_read_b128 v[128:131], v156
	ds_read_b128 v[140:143], v156 offset:1024
	ds_read_b128 v[152:155], v156 offset:2048
	ds_read_b128 v[156:159], v156 offset:3072
	ds_read_b128 v[168:171], v180
	ds_read_b128 v[172:175], v180 offset:1024
	ds_read_b128 v[176:179], v180 offset:2048
	ds_read_b128 v[180:183], v180 offset:3072
	s_add_i32 s11, s8, 0xffea4000
	s_cmpk_eq_i32 s10, 0x54
	s_cselect_b32 s13, s6, s11
	s_cselect_b32 s12, s7, s9
	s_or_b32 s11, s13, 0x4000
	ds_read_b128 v[184:187], v223
	ds_read_b128 v[188:191], v223 offset:1024
	ds_read_b128 v[192:195], v223 offset:2048
	ds_read_b128 v[196:199], v223 offset:3072
	ds_read_b128 v[200:203], v223 offset:4096
	ds_read_b128 v[204:207], v223 offset:5120
	ds_read_b128 v[224:227], v223 offset:6144
	ds_read_b128 v[228:231], v223 offset:7168
	s_mov_b32 m0, s87
	s_nop 0
	buffer_load_dwordx4 v220, s[20:23], s8 offen lds
	s_mov_b32 m0, s89
	s_nop 0
	buffer_load_dwordx4 v221, s[20:23], s8 offen lds
	s_waitcnt vmcnt(8)
	s_waitcnt lgkmcnt(0)
	s_barrier
	s_setprio 1
	s_waitcnt lgkmcnt(7)
	v_mfma_f32_16x16x32_bf16 v[164:167], v[128:131], v[184:187], v[164:167]
	v_mfma_f32_16x16x32_bf16 v[160:163], v[152:155], v[184:187], v[160:163]
	s_waitcnt lgkmcnt(5)
	v_mfma_f32_16x16x32_bf16 v[136:139], v[128:131], v[192:195], v[136:139]
	v_mfma_f32_16x16x32_bf16 v[132:135], v[152:155], v[192:195], v[132:135]
	s_waitcnt lgkmcnt(3)
	v_mfma_f32_16x16x32_bf16 v[116:119], v[128:131], v[200:203], v[116:119]
	v_mfma_f32_16x16x32_bf16 v[112:115], v[152:155], v[200:203], v[112:115]
	s_waitcnt lgkmcnt(1)
	v_mfma_f32_16x16x32_bf16 v[76:79], v[128:131], v[224:227], v[76:79]
	v_mfma_f32_16x16x32_bf16 v[72:75], v[152:155], v[224:227], v[72:75]
	v_mfma_f32_16x16x32_bf16 v[164:167], v[140:143], v[188:191], v[164:167]
	v_mfma_f32_16x16x32_bf16 v[160:163], v[156:159], v[188:191], v[160:163]
	v_mfma_f32_16x16x32_bf16 v[136:139], v[140:143], v[196:199], v[136:139]
	v_mfma_f32_16x16x32_bf16 v[132:135], v[156:159], v[196:199], v[132:135]
	v_mfma_f32_16x16x32_bf16 v[116:119], v[140:143], v[204:207], v[116:119]
	v_mfma_f32_16x16x32_bf16 v[112:115], v[156:159], v[204:207], v[112:115]
	s_waitcnt lgkmcnt(0)
	v_mfma_f32_16x16x32_bf16 v[76:79], v[140:143], v[228:231], v[76:79]
	v_mfma_f32_16x16x32_bf16 v[72:75], v[156:159], v[228:231], v[72:75]
	s_setprio 0
	s_setprio 1
	v_mfma_f32_16x16x32_bf16 v[148:151], v[168:171], v[184:187], v[148:151]
	v_mfma_f32_16x16x32_bf16 v[144:147], v[176:179], v[184:187], v[144:147]
	v_mfma_f32_16x16x32_bf16 v[124:127], v[168:171], v[192:195], v[124:127]
	v_mfma_f32_16x16x32_bf16 v[120:123], v[176:179], v[192:195], v[120:123]
	v_mfma_f32_16x16x32_bf16 v[108:111], v[168:171], v[200:203], v[108:111]
	v_mfma_f32_16x16x32_bf16 v[104:107], v[176:179], v[200:203], v[104:107]
	v_mfma_f32_16x16x32_bf16 v[68:71], v[168:171], v[224:227], v[68:71]
	v_mfma_f32_16x16x32_bf16 v[64:67], v[176:179], v[224:227], v[64:67]
	v_mfma_f32_16x16x32_bf16 v[148:151], v[172:175], v[188:191], v[148:151]
	v_mfma_f32_16x16x32_bf16 v[144:147], v[180:183], v[188:191], v[144:147]
	v_mfma_f32_16x16x32_bf16 v[124:127], v[172:175], v[196:199], v[124:127]
	v_mfma_f32_16x16x32_bf16 v[120:123], v[180:183], v[196:199], v[120:123]
	v_mfma_f32_16x16x32_bf16 v[108:111], v[172:175], v[204:207], v[108:111]
	v_mfma_f32_16x16x32_bf16 v[104:107], v[180:183], v[204:207], v[104:107]
	v_mfma_f32_16x16x32_bf16 v[68:71], v[172:175], v[228:231], v[68:71]
	v_mfma_f32_16x16x32_bf16 v[64:67], v[180:183], v[228:231], v[64:67]
	s_setprio 0
	s_barrier
	ds_read_b128 v[184:187], v223 offset:16384
	ds_read_b128 v[188:191], v223 offset:17408
	ds_read_b128 v[192:195], v223 offset:18432
	ds_read_b128 v[196:199], v223 offset:19456
	ds_read_b128 v[200:203], v223 offset:20480
	ds_read_b128 v[204:207], v223 offset:21504
	ds_read_b128 v[224:227], v223 offset:22528
	ds_read_b128 v[228:231], v223 offset:23552
	s_mov_b32 m0, s51
	s_nop 0
	buffer_load_dwordx4 v220, s[52:55], s12 offen lds
	s_add_i32 s14, s12, 0x160000
	s_mov_b32 m0, s74
	s_nop 0
	buffer_load_dwordx4 v221, s[52:55], s12 offen lds
	s_mov_b32 m0, s75
	s_nop 0
	buffer_load_dwordx4 v220, s[52:55], s14 offen lds
	s_mov_b32 m0, s76
	s_nop 0
	buffer_load_dwordx4 v221, s[52:55], s14 offen lds
	s_mov_b32 m0, s31
	s_nop 0
	buffer_load_dwordx4 v220, s[20:23], s13 offen lds
	s_mov_b32 m0, s77
	s_nop 0
	buffer_load_dwordx4 v221, s[20:23], s13 offen lds
	s_waitcnt vmcnt(8)
	s_waitcnt lgkmcnt(0)
	s_barrier
	s_setprio 1
	s_waitcnt lgkmcnt(7)
	v_mfma_f32_16x16x32_bf16 v[60:63], v[128:131], v[184:187], v[60:63]
	v_mfma_f32_16x16x32_bf16 v[56:59], v[152:155], v[184:187], v[56:59]
	s_waitcnt lgkmcnt(5)
	v_mfma_f32_16x16x32_bf16 v[44:47], v[128:131], v[192:195], v[44:47]
	v_mfma_f32_16x16x32_bf16 v[40:43], v[152:155], v[192:195], v[40:43]
	s_waitcnt lgkmcnt(3)
	v_mfma_f32_16x16x32_bf16 v[28:31], v[128:131], v[200:203], v[28:31]
	v_mfma_f32_16x16x32_bf16 v[24:27], v[152:155], v[200:203], v[24:27]
	s_waitcnt lgkmcnt(1)
	v_mfma_f32_16x16x32_bf16 v[12:15], v[128:131], v[224:227], v[12:15]
	v_mfma_f32_16x16x32_bf16 v[8:11], v[152:155], v[224:227], v[8:11]
	v_mfma_f32_16x16x32_bf16 v[60:63], v[140:143], v[188:191], v[60:63]
	v_mfma_f32_16x16x32_bf16 v[56:59], v[156:159], v[188:191], v[56:59]
	v_mfma_f32_16x16x32_bf16 v[44:47], v[140:143], v[196:199], v[44:47]
	v_mfma_f32_16x16x32_bf16 v[40:43], v[156:159], v[196:199], v[40:43]
	v_mfma_f32_16x16x32_bf16 v[28:31], v[140:143], v[204:207], v[28:31]
	v_mfma_f32_16x16x32_bf16 v[24:27], v[156:159], v[204:207], v[24:27]
	s_waitcnt lgkmcnt(0)
	v_mfma_f32_16x16x32_bf16 v[12:15], v[140:143], v[228:231], v[12:15]
	v_mfma_f32_16x16x32_bf16 v[8:11], v[156:159], v[228:231], v[8:11]
	s_setprio 0
	s_setprio 1
	v_mfma_f32_16x16x32_bf16 v[52:55], v[168:171], v[184:187], v[52:55]
	v_mfma_f32_16x16x32_bf16 v[48:51], v[176:179], v[184:187], v[48:51]
	v_mfma_f32_16x16x32_bf16 v[36:39], v[168:171], v[192:195], v[36:39]
	v_mfma_f32_16x16x32_bf16 v[32:35], v[176:179], v[192:195], v[32:35]
	v_mfma_f32_16x16x32_bf16 v[20:23], v[168:171], v[200:203], v[20:23]
	v_mfma_f32_16x16x32_bf16 v[16:19], v[176:179], v[200:203], v[16:19]
	v_mfma_f32_16x16x32_bf16 v[4:7], v[168:171], v[224:227], v[4:7]
	v_mfma_f32_16x16x32_bf16 v[0:3], v[176:179], v[224:227], v[0:3]
	v_mfma_f32_16x16x32_bf16 v[52:55], v[172:175], v[188:191], v[52:55]
	v_mfma_f32_16x16x32_bf16 v[48:51], v[180:183], v[188:191], v[48:51]
	v_mfma_f32_16x16x32_bf16 v[36:39], v[172:175], v[196:199], v[36:39]
	v_mfma_f32_16x16x32_bf16 v[32:35], v[180:183], v[196:199], v[32:35]
	v_mfma_f32_16x16x32_bf16 v[20:23], v[172:175], v[204:207], v[20:23]
	v_mfma_f32_16x16x32_bf16 v[16:19], v[180:183], v[204:207], v[16:19]
	v_mfma_f32_16x16x32_bf16 v[4:7], v[172:175], v[228:231], v[4:7]
	v_mfma_f32_16x16x32_bf16 v[0:3], v[180:183], v[228:231], v[0:3]
	s_setprio 0
	s_barrier
	v_add_u32_e32 v156, 0x18000, v222
	v_add_u32_e32 v180, 0x1c000, v222
	ds_read_b128 v[128:131], v156
	ds_read_b128 v[140:143], v156 offset:1024
	ds_read_b128 v[152:155], v156 offset:2048
	ds_read_b128 v[156:159], v156 offset:3072
	ds_read_b128 v[168:171], v180
	ds_read_b128 v[172:175], v180 offset:1024
	ds_read_b128 v[176:179], v180 offset:2048
	ds_read_b128 v[180:183], v180 offset:3072
	ds_read_b128 v[184:187], v223 offset:32768
	ds_read_b128 v[188:191], v223 offset:33792
	ds_read_b128 v[192:195], v223 offset:34816
	ds_read_b128 v[196:199], v223 offset:35840
	ds_read_b128 v[200:203], v223 offset:36864
	ds_read_b128 v[204:207], v223 offset:37888
	ds_read_b128 v[224:227], v223 offset:38912
	ds_read_b128 v[228:231], v223 offset:39936
	s_add_i32 s13, s13, 0x160000
	s_mov_b32 m0, s78
	s_nop 0
	buffer_load_dwordx4 v220, s[20:23], s13 offen lds
	s_mov_b32 m0, s79
	s_nop 0
	buffer_load_dwordx4 v221, s[20:23], s13 offen lds
	s_waitcnt vmcnt(8)
	s_waitcnt lgkmcnt(0)
	s_barrier
	s_setprio 1
	s_waitcnt lgkmcnt(7)
	v_mfma_f32_16x16x32_bf16 v[164:167], v[128:131], v[184:187], v[164:167]
	v_mfma_f32_16x16x32_bf16 v[160:163], v[152:155], v[184:187], v[160:163]
	s_waitcnt lgkmcnt(5)
	v_mfma_f32_16x16x32_bf16 v[136:139], v[128:131], v[192:195], v[136:139]
	v_mfma_f32_16x16x32_bf16 v[132:135], v[152:155], v[192:195], v[132:135]
	s_waitcnt lgkmcnt(3)
	v_mfma_f32_16x16x32_bf16 v[116:119], v[128:131], v[200:203], v[116:119]
	v_mfma_f32_16x16x32_bf16 v[112:115], v[152:155], v[200:203], v[112:115]
	s_waitcnt lgkmcnt(1)
	v_mfma_f32_16x16x32_bf16 v[76:79], v[128:131], v[224:227], v[76:79]
	v_mfma_f32_16x16x32_bf16 v[72:75], v[152:155], v[224:227], v[72:75]
	v_mfma_f32_16x16x32_bf16 v[164:167], v[140:143], v[188:191], v[164:167]
	v_mfma_f32_16x16x32_bf16 v[160:163], v[156:159], v[188:191], v[160:163]
	v_mfma_f32_16x16x32_bf16 v[136:139], v[140:143], v[196:199], v[136:139]
	v_mfma_f32_16x16x32_bf16 v[132:135], v[156:159], v[196:199], v[132:135]
	v_mfma_f32_16x16x32_bf16 v[116:119], v[140:143], v[204:207], v[116:119]
	v_mfma_f32_16x16x32_bf16 v[112:115], v[156:159], v[204:207], v[112:115]
	s_waitcnt lgkmcnt(0)
	v_mfma_f32_16x16x32_bf16 v[76:79], v[140:143], v[228:231], v[76:79]
	v_mfma_f32_16x16x32_bf16 v[72:75], v[156:159], v[228:231], v[72:75]
	s_setprio 0
	s_setprio 1
	v_mfma_f32_16x16x32_bf16 v[148:151], v[168:171], v[184:187], v[148:151]
	v_mfma_f32_16x16x32_bf16 v[144:147], v[176:179], v[184:187], v[144:147]
	v_mfma_f32_16x16x32_bf16 v[124:127], v[168:171], v[192:195], v[124:127]
	v_mfma_f32_16x16x32_bf16 v[120:123], v[176:179], v[192:195], v[120:123]
	v_mfma_f32_16x16x32_bf16 v[108:111], v[168:171], v[200:203], v[108:111]
	v_mfma_f32_16x16x32_bf16 v[104:107], v[176:179], v[200:203], v[104:107]
	v_mfma_f32_16x16x32_bf16 v[68:71], v[168:171], v[224:227], v[68:71]
	v_mfma_f32_16x16x32_bf16 v[64:67], v[176:179], v[224:227], v[64:67]
	v_mfma_f32_16x16x32_bf16 v[148:151], v[172:175], v[188:191], v[148:151]
	v_mfma_f32_16x16x32_bf16 v[144:147], v[180:183], v[188:191], v[144:147]
	v_mfma_f32_16x16x32_bf16 v[124:127], v[172:175], v[196:199], v[124:127]
	v_mfma_f32_16x16x32_bf16 v[120:123], v[180:183], v[196:199], v[120:123]
	v_mfma_f32_16x16x32_bf16 v[108:111], v[172:175], v[204:207], v[108:111]
	v_mfma_f32_16x16x32_bf16 v[104:107], v[180:183], v[204:207], v[104:107]
	v_mfma_f32_16x16x32_bf16 v[68:71], v[172:175], v[228:231], v[68:71]
	v_mfma_f32_16x16x32_bf16 v[64:67], v[180:183], v[228:231], v[64:67]
	s_setprio 0
	s_barrier
	ds_read_b128 v[184:187], v223 offset:49152
	ds_read_b128 v[188:191], v223 offset:50176
	ds_read_b128 v[192:195], v223 offset:51200
	ds_read_b128 v[196:199], v223 offset:52224
	ds_read_b128 v[200:203], v223 offset:53248
	ds_read_b128 v[204:207], v223 offset:54272
	ds_read_b128 v[224:227], v223 offset:55296
	ds_read_b128 v[228:231], v223 offset:56320
	s_or_b32 s13, s12, 0x4000
	s_mov_b32 m0, s34
	s_nop 0
	buffer_load_dwordx4 v220, s[52:55], s13 offen lds
	s_add_i32 s12, s12, 0x164000
	s_mov_b32 m0, s82
	s_nop 0
	buffer_load_dwordx4 v221, s[52:55], s13 offen lds
	s_mov_b32 m0, s85
	s_nop 0
	buffer_load_dwordx4 v220, s[52:55], s12 offen lds
	s_mov_b32 m0, s86
	s_nop 0
	buffer_load_dwordx4 v221, s[52:55], s12 offen lds
	s_mov_b32 m0, s83
	s_nop 0
	buffer_load_dwordx4 v220, s[20:23], s11 offen lds
	s_mov_b32 m0, s84
	s_nop 0
	buffer_load_dwordx4 v221, s[20:23], s11 offen lds
	s_waitcnt vmcnt(8)
	s_waitcnt lgkmcnt(0)
	s_barrier
	s_setprio 1
	s_waitcnt lgkmcnt(7)
	v_mfma_f32_16x16x32_bf16 v[60:63], v[128:131], v[184:187], v[60:63]
	v_mfma_f32_16x16x32_bf16 v[56:59], v[152:155], v[184:187], v[56:59]
	s_waitcnt lgkmcnt(5)
	v_mfma_f32_16x16x32_bf16 v[44:47], v[128:131], v[192:195], v[44:47]
	v_mfma_f32_16x16x32_bf16 v[40:43], v[152:155], v[192:195], v[40:43]
	s_waitcnt lgkmcnt(3)
	v_mfma_f32_16x16x32_bf16 v[28:31], v[128:131], v[200:203], v[28:31]
	v_mfma_f32_16x16x32_bf16 v[24:27], v[152:155], v[200:203], v[24:27]
	s_waitcnt lgkmcnt(1)
	v_mfma_f32_16x16x32_bf16 v[12:15], v[128:131], v[224:227], v[12:15]
	v_mfma_f32_16x16x32_bf16 v[8:11], v[152:155], v[224:227], v[8:11]
	v_mfma_f32_16x16x32_bf16 v[60:63], v[140:143], v[188:191], v[60:63]
	v_mfma_f32_16x16x32_bf16 v[56:59], v[156:159], v[188:191], v[56:59]
	v_mfma_f32_16x16x32_bf16 v[44:47], v[140:143], v[196:199], v[44:47]
	v_mfma_f32_16x16x32_bf16 v[40:43], v[156:159], v[196:199], v[40:43]
	v_mfma_f32_16x16x32_bf16 v[28:31], v[140:143], v[204:207], v[28:31]
	v_mfma_f32_16x16x32_bf16 v[24:27], v[156:159], v[204:207], v[24:27]
	s_waitcnt lgkmcnt(0)
	v_mfma_f32_16x16x32_bf16 v[12:15], v[140:143], v[228:231], v[12:15]
	v_mfma_f32_16x16x32_bf16 v[8:11], v[156:159], v[228:231], v[8:11]
	s_setprio 0
	s_setprio 1
	v_mfma_f32_16x16x32_bf16 v[52:55], v[168:171], v[184:187], v[52:55]
	v_mfma_f32_16x16x32_bf16 v[48:51], v[176:179], v[184:187], v[48:51]
	v_mfma_f32_16x16x32_bf16 v[36:39], v[168:171], v[192:195], v[36:39]
	v_mfma_f32_16x16x32_bf16 v[32:35], v[176:179], v[192:195], v[32:35]
	v_mfma_f32_16x16x32_bf16 v[20:23], v[168:171], v[200:203], v[20:23]
	v_mfma_f32_16x16x32_bf16 v[16:19], v[176:179], v[200:203], v[16:19]
	v_mfma_f32_16x16x32_bf16 v[4:7], v[168:171], v[224:227], v[4:7]
	v_mfma_f32_16x16x32_bf16 v[0:3], v[176:179], v[224:227], v[0:3]
	v_mfma_f32_16x16x32_bf16 v[52:55], v[172:175], v[188:191], v[52:55]
	v_mfma_f32_16x16x32_bf16 v[48:51], v[180:183], v[188:191], v[48:51]
	v_mfma_f32_16x16x32_bf16 v[36:39], v[172:175], v[196:199], v[36:39]
	v_mfma_f32_16x16x32_bf16 v[32:35], v[180:183], v[196:199], v[32:35]
	v_mfma_f32_16x16x32_bf16 v[20:23], v[172:175], v[204:207], v[20:23]
	v_mfma_f32_16x16x32_bf16 v[16:19], v[180:183], v[204:207], v[16:19]
	v_mfma_f32_16x16x32_bf16 v[4:7], v[172:175], v[228:231], v[4:7]
	v_mfma_f32_16x16x32_bf16 v[0:3], v[180:183], v[228:231], v[0:3]
	s_setprio 0
	s_barrier
	s_add_i32 s10, s10, 2
	s_add_i32 s8, s8, 0x8000
	s_add_i32 s9, s9, 0x8000
	s_cmpk_gt_u32 s10, 0x55
	s_cbranch_scc0 .LBB0_885
	s_and_b64 vcc, exec, s[2:3]
	s_cbranch_vccz .LBB0_888
	s_barrier
